# MLA loop: one barrier per tile (V lags K by one tile), softmax VALU interleaved under PV MFMAs, waves 4-7 run a reordered anti-phase body
# speedup vs baseline: 1.0177x; 1.0177x over previous
; __device__ __forceinline__ int fresh_tid() { int t = threadIdx.x; asm volatile("" : "+v"(t)); return t; }
; __device__ __forceinline__ int v_st(int k, int c) { const int kk = (k & ~0xC) | ((k & 4) << 1) | ((k & 8) >> 1); return ((kk >> 3) * 4 + (c >> 5)) * 512 + ((kk & 7) * 32 + (c & 31)) * 2; }
; __device__ __forceinline__ int v_rd_base(int lane) { return ((lane & 3) << 3) | (((lane >> 2) & 3) << 6) | (((lane >> 4) & 1) << 5) | (((lane >> 5) & 1) << 8); }
; #define SLOAD(i, j) do { const long kr_ = KROW(j); sr_[i].vs0 = ld8(Vp + (kr_ + sr) * ldv + sc); sr_[i].ks0 = ld8(Kp + (kr_ + sr) * ldk + sc); \
;     if (DQK == 96) sr_[i].ks1 = ld8(Kp + (kr_ + sr2) * ldk + sc2); } while (0)
; #define SWRITE(b, i) do { *(bf16x8*)(V_lds + (b) * SHM_V + vst0) = sr_[i].vs0; *(bf16x8*)(K_lds + (b) * SHM_K + kst0) = sr_[i].ks0; \
;     if (DQK == 96) *(bf16x8*)(K_lds + (b) * SHM_K + kst1) = sr_[i].ks1; } while (0)
; template <int DQK, int MODE, int ldq, int ldk, int ldv> ...
;     ...
;   const int tid = fresh_tid(), wid = tid >> 6, lane = tid & 63, r32 = lane & 31, hi = lane >> 5;
;   char* V_lds = lds; char* K_lds = lds + 2 * SHM_V;
;   float* ws = (float*)(lds + 2 * SHM_V + 2 * SHM_K) + wid * 64; float* li_l = ws; float* al_l = ws + 32;
;   float m_reg = -1e30f, l_reg = 0; f32x16 o[2] = {}; bf16x8 qr[DQK / 16];
;   const bf16_t* Qw = Qb + (long)(wid * QBLK + r32) * ldq + hi * 8;
; #pragma unroll
;   for (int d0 = 0; d0 < DQK / 16; ++d0) qr[d0] = ld8(Qw + d0 * 16);
;   NaInfo na; na.brow = (const float*)(lds + rpb_off); na.qr = r0 + (wid >> 1); na.qc = (wid & 1) * 32 + r32;
;   const int sr = tid >> 3, sc = (tid & 7) * 8, vst0 = v_st(sr, sc), kst0 = KSWZ(sr, sc * 2);
;   const int sr2 = (tid & 255) >> 2, sc2 = 64 + (tid & 3) * 8, kst1 = KSWZ(sr2, sc2 * 2);
;   const int vb0 = (int)(uintptr_t)V_lds + v_rd_base(lane);
;   struct { bf16x8 vs0, ks0, ks1; } sr_[2];
;     ...
;   f32x16 pA0, pA1, pB0, pB1; float mnA, mnB, alA, alB; bf16x8 pa0, pa1, pa2, pa3;
;   constexpr int SE = 0, SO = 1;
;   SLOAD(SE, 0); SLOAD(SO, 1); asm volatile("s_waitcnt vmcnt(0)" ::: "memory"); SWRITE(0, SE); SWRITE(1, SO);
;   if (2 < NT) SLOAD(SE, 2);
;   __syncthreads();
.LBB0_299:
	v_readfirstlane_b32 s32, v234
	s_nop 0
	s_lshr_b32 s32, s32, 8
	s_ashr_i32 s11, s22, 7
	s_lshl_b32 s0, s22, 8
	s_lshl_b32 s10, s11, 13
	s_and_b32 s0, s0, 0x1f00
	s_or_b32 s6, s10, s0
	s_bfe_u32 s4, s22, 0x20005
	s_ashr_i32 s7, s6, 31
	s_mul_i32 s1, s6, 0x300
	s_mul_hi_i32 s0, s6, 0x300
	s_add_u32 s1, s16, s1
	s_addc_u32 s0, s17, s0
	s_mul_i32 s5, s4, 0xc0
	s_add_u32 s12, s1, s5
	s_addc_u32 s13, s0, 0
	s_add_u32 s0, s18, s5
	s_addc_u32 s1, s19, 0
	s_lshl_b32 s23, s4, 6
	s_lshl_b32 s4, s4, 7
	s_add_u32 s4, s20, s4
	s_addc_u32 s5, s21, 0
	s_lshl_b32 s24, s11, 8
	s_add_i32 s24, s24, 0x8000
	v_mov_b32_e32 v52, v234
	s_add_i32 s26, 0, 0x10000
	s_cmp_lg_u32 0, -1
	v_ashrrev_i32_e32 v130, 3, v52
	v_lshlrev_b32_e32 v28, 3, v52
	v_and_b32_e32 v0, 56, v28
	v_bfe_u32 v132, v52, 2, 6
	s_cselect_b32 s25, 0, 0
	s_ashr_i32 s11, s10, 31
	v_ashrrev_i32_e32 v131, 31, v130
	s_waitcnt lgkmcnt(0)
	v_lshlrev_b32_e32 v48, 1, v0
	v_lshl_add_u64 v[0:1], v[130:131], 0, s[10:11]
	v_mov_b64_e32 v[24:25], s[0:1]
	v_or_b32_e32 v8, s10, v132
	v_mad_u64_u32 v[4:5], s[28:29], v0, s70, v[24:25]
	v_mad_i64_i32 v[8:9], s[28:29], v8, s70, v[24:25]
	s_or_b32 s28, s10, 64
	s_ashr_i32 s29, s28, 31
	v_lshl_add_u64 v[16:17], v[130:131], 0, s[28:29]
	v_lshlrev_b64 v[2:3], 9, v[0:1]
	v_mad_u64_u32 v[18:19], s[30:31], v16, s70, v[24:25]
	v_lshl_add_u64 v[2:3], s[4:5], 0, v[2:3]
	v_mov_b32_e32 v49, v205
	v_mad_i32_i24 v5, v1, s70, v5
	v_mad_i32_i24 v19, v17, s70, v19
	v_lshlrev_b32_e32 v53, 4, v52
	v_lshl_add_u64 v[2:3], v[2:3], 0, v[48:49]
	v_lshl_add_u64 v[4:5], v[4:5], 0, v[48:49]
	v_lshlrev_b64 v[10:11], 9, v[16:17]
	v_lshl_add_u64 v[16:17], v[18:19], 0, v[48:49]
	v_or_b32_e32 v18, s28, v132
	v_and_b32_e32 v50, 48, v53
	global_load_dwordx4 v[0:3], v[2:3], off
	s_nop 0
	global_load_dwordx4 v[4:7], v[4:5], off
	v_mov_b32_e32 v51, v205
	v_lshl_add_u64 v[10:11], s[4:5], 0, v[10:11]
	v_mad_i64_i32 v[18:19], s[28:29], v18, s70, v[24:25]
	v_lshl_add_u64 v[8:9], v[8:9], 0, v[50:51]
	v_lshl_add_u64 v[12:13], v[10:11], 0, v[48:49]
	v_lshl_add_u64 v[20:21], v[18:19], 0, v[50:51]
	global_load_dwordx4 v[8:11], v[8:9], off offset:128
	s_nop 0
	global_load_dwordx4 v[12:15], v[12:13], off
	s_nop 0
	global_load_dwordx4 v[16:19], v[16:17], off
	s_nop 0
	global_load_dwordx4 v[20:23], v[20:21], off offset:128
	v_ashrrev_i32_e32 v54, 1, v52
	s_movk_i32 s11, 0xffe0
	v_bfe_u32 v133, v52, 5, 1
	v_bfi_b32 v29, s11, v54, v52
	v_mov_b64_e32 v[26:27], s[12:13]
	v_mad_i64_i32 v[26:27], s[12:13], v29, s70, v[26:27]
	v_lshlrev_b32_e32 v204, 4, v133
	v_lshl_add_u64 v[26:27], v[26:27], 0, v[204:205]
	global_load_dwordx4 v[84:87], v[26:27], off
	global_load_dwordx4 v[80:83], v[26:27], off offset:32
	global_load_dwordx4 v[76:79], v[26:27], off offset:64
	global_load_dwordx4 v[72:75], v[26:27], off offset:96
	global_load_dwordx4 v[68:71], v[26:27], off offset:128
	global_load_dwordx4 v[64:67], v[26:27], off offset:160
	v_and_b32_e32 v26, 0xfffff0, v130
	v_lshlrev_b32_e32 v27, 1, v130
	v_and_or_b32 v26, v27, 8, v26
	v_lshrrev_b32_e32 v26, 1, v26
	v_bfe_u32 v28, v28, 5, 1
	v_lshrrev_b32_e32 v27, 1, v130
	v_or_b32_e32 v26, v26, v28
	v_and_b32_e32 v28, 3, v130
	v_and_or_b32 v27, v27, 4, v28
	v_and_b32_e32 v28, 48, v48
	v_lshl_or_b32 v27, v27, 6, v28
	v_lshlrev_b32_e32 v28, 4, v130
	v_lshl_or_b32 v26, v26, 9, v27
	v_lshlrev_b32_e32 v27, 8, v130
	v_and_b32_e32 v28, 0xf0, v28
	s_or_b32 s12, s10, 0x80
	v_bitop3_b32 v27, v48, v27, v28 bitop3:0xde
	v_lshlrev_b32_e32 v30, 2, v52
	v_add_u32_e32 v145, 0, v26
	s_ashr_i32 s13, s12, 31
	v_lshlrev_b32_e32 v28, 8, v132
	v_or_b32_e32 v29, 0x80, v50
	v_and_b32_e32 v30, 0xf0, v30
	s_waitcnt vmcnt(0)
	v_add_u32_e32 v146, 0, v27
	v_bitop3_b32 v28, v29, v28, v30 bitop3:0xde
	v_add_u32_e32 v147, 0, v28
	v_and_b32_e32 v140, 31, v52
	v_and_b32_e32 v56, 63, v52
	v_and_b32_e32 v128, 0xffffffe0, v54
	v_readlane_b32 s76, v255, 19
	v_readlane_b32 s77, v255, 20
	v_readlane_b32 s78, v255, 21
	v_readlane_b32 s79, v255, 22
	v_readlane_b32 s80, v255, 23
	v_readlane_b32 s81, v255, 24
	v_readlane_b32 s82, v255, 25
	v_readlane_b32 s83, v255, 26
	v_readlane_b32 s84, v255, 27
	v_readlane_b32 s85, v255, 28
	v_readlane_b32 s86, v255, 29
	v_readlane_b32 s87, v255, 30
	v_readlane_b32 s88, v255, 31
	v_readlane_b32 s89, v255, 32
	v_readlane_b32 s90, v255, 33
	v_readlane_b32 s91, v255, 34
	s_mov_b32 s76, s77
	s_mov_b32 s78, s77
	s_mov_b32 s79, s77
	s_mov_b32 s80, s77
	s_mov_b32 s81, s77
	s_mov_b32 s82, s77
	s_mov_b32 s83, s77
	s_mov_b32 s84, s77
	s_mov_b32 s85, s77
	s_mov_b32 s86, s77
	s_mov_b32 s87, s77
	s_mov_b32 s88, s77
	s_waitcnt vmcnt(0)
	ds_write_b128 v145, v[0:3]
	v_lshl_add_u64 v[0:1], v[130:131], 0, s[12:13]
	ds_write_b128 v146, v[4:7] offset:32768
	v_lshlrev_b64 v[2:3], 9, v[0:1]
	v_mad_u64_u32 v[4:5], s[28:29], v0, s70, v[24:25]
	v_lshl_add_u64 v[2:3], s[4:5], 0, v[2:3]
	v_mad_i32_i24 v5, v1, s70, v5
	ds_write_b128 v147, v[8:11] offset:32768
	ds_write_b128 v145, v[12:15] offset:16384
	ds_write_b128 v146, v[16:19] offset:49152
	ds_write_b128 v147, v[20:23] offset:49152
	v_lshl_add_u64 v[2:3], v[2:3], 0, v[48:49]
	s_mov_b32 s98, 0xffff8000
	s_mov_b32 s99, -1
	v_lshl_add_u64 v[2:3], v[2:3], 0, s[98:99]
	v_lshl_add_u64 v[0:1], v[4:5], 0, v[48:49]
	global_load_dwordx4 v[92:95], v[2:3], off
	global_load_dwordx4 v[88:91], v[0:1], off
	v_or_b32_e32 v0, s12, v132
	v_mad_i64_i32 v[0:1], s[12:13], v0, s70, v[24:25]
	v_lshl_add_u64 v[0:1], v[0:1], 0, v[50:51]
	v_lshlrev_b32_e32 v8, 8, v140
	v_and_b32_e32 v9, 0xf0, v53
	global_load_dwordx4 v[96:99], v[0:1], off offset:128
	v_bitop3_b32 v0, v204, v8, v9 bitop3:0xde
	v_add_u32_e32 v148, 0, v0
	s_waitcnt lgkmcnt(0)
	s_barrier
; template <int DQK> __device__ __forceinline__ void partialSM(f32x16& p0, f32x16& p1, float& m_reg, float& mn, float& alpha) {
;   constexpr float SCALE = (DQK == 96) ? 0.10206207261596577f : 0.125f;
;   constexpr float C = SCALE * 1.4426950408889634f;
;   float pmax = p0[0];
; #pragma unroll
;   for (int r = 1; r < 16; ++r) pmax = fmaxf(pmax, p0[r]);
; #pragma unroll
;   for (int r = 0; r < 16; ++r) pmax = fmaxf(pmax, p1[r]);
;   { auto rr = __builtin_amdgcn_permlane32_swap(__float_as_uint(pmax), __float_as_uint(pmax), false, false);
;     pmax = fmaxf(__uint_as_float(rr[0]), __uint_as_float(rr[1])); }
;   if (__builtin_expect(__all(pmax - m_reg <= THR / SCALE), 1)) { mn = m_reg; alpha = 1.f; }
;   else { mn = fmaxf(m_reg, pmax); alpha = __builtin_amdgcn_exp2f((m_reg - mn) * C); m_reg = mn; }
;   float mnC = -mn * C;
; #pragma unroll
;   for (int r = 0; r < 16; ++r) p0[r] = fmaf(p0[r], C, mnC);
; #pragma unroll
;   for (int r = 0; r < 16; ++r) p1[r] = fmaf(p1[r], C, mnC);
; #pragma unroll
;   for (int r = 0; r < 16; ++r) p0[r] = __builtin_amdgcn_exp2f(p0[r]);
; }
; template <int DQK> __device__ __forceinline__ void qkt(f32x16& p0, f32x16& p1, const char* Ks, const bf16x8* qr, int r32, int hi) {
;   p0 = f32x16{}; p1 = f32x16{};
; #pragma unroll
;   for (int d0 = 0; d0 < DQK / 16; ++d0) { int cb = (d0 * 16 + hi * 8) * 2;
;     bf16x8 b0 = *reinterpret_cast<const bf16x8*>(Ks + KSWZ(r32, cb));
;     bf16x8 b1 = *reinterpret_cast<const bf16x8*>(Ks + KSWZ(32 + r32, cb));
;     p0 = __builtin_amdgcn_mfma_f32_32x32x16_bf16(b0, qr[d0], p0, 0, 0, 0);
;     p1 = __builtin_amdgcn_mfma_f32_32x32x16_bf16(b1, qr[d0], p1, 0, 0, 0); }
; }
	ds_read_b128 v[0:3], v148 offset:32768
	ds_read_b128 v[4:7], v148 offset:40960
	s_waitcnt lgkmcnt(1)
	v_mfma_f32_32x32x16_bf16 v[32:47], v[0:3], v[84:87], 0
	v_or_b32_e32 v0, 32, v204
	v_bitop3_b32 v0, v0, v8, v9 bitop3:0xde
	v_add_u32_e32 v152, 0, v0
	v_lshlrev_b32_e32 v10, 3, v56
	v_and_b32_e32 v11, 0xc0, v53
	s_mov_b32 s89, s77
	s_mov_b32 s90, s77
	s_waitcnt lgkmcnt(0)
	v_mfma_f32_32x32x16_bf16 v[16:31], v[4:7], v[84:87], 0
	ds_read_b128 v[0:3], v152 offset:32768
	ds_read_b128 v[4:7], v152 offset:40960
	s_mov_b32 s91, s77
	v_lshl_add_u64 v[134:135], s[4:5], 0, v[48:49]
	v_lshl_add_u64 v[136:137], s[0:1], 0, v[48:49]
	s_mov_b32 s13, s77
	s_mov_b32 s11, 4
	v_lshl_add_u64 v[138:139], s[0:1], 0, v[50:51]
	s_waitcnt lgkmcnt(1)
	v_mfma_f32_32x32x16_bf16 v[32:47], v[0:3], v[80:83], v[32:47]
	v_or_b32_e32 v0, 64, v204
	v_bitop3_b32 v0, v0, v8, v9 bitop3:0xde
	v_add_u32_e32 v151, 0, v0
	v_cmp_gt_u32_e64 s[4:5], 32, v56
	v_mov_b32_e32 v142, 0
	s_waitcnt lgkmcnt(0)
	v_mfma_f32_32x32x16_bf16 v[16:31], v[4:7], v[80:83], v[16:31]
	ds_read_b128 v[0:3], v151 offset:32768
	ds_read_b128 v[4:7], v151 offset:40960
	s_waitcnt lgkmcnt(1)
	v_mfma_f32_32x32x16_bf16 v[32:47], v[0:3], v[76:79], v[32:47]
	v_or_b32_e32 v0, 0x60, v204
	v_bitop3_b32 v0, v0, v8, v9 bitop3:0xde
	v_add_u32_e32 v149, 0, v0
	ds_read_b128 v[0:3], v149 offset:32768
	s_waitcnt lgkmcnt(1)
	v_mfma_f32_32x32x16_bf16 v[16:31], v[4:7], v[76:79], v[16:31]
	v_and_b32_e32 v4, 0x3fffffc0, v52
	v_lshl_add_u32 v57, v4, 2, s26
	ds_read_b128 v[4:7], v149 offset:40960
	v_lshl_add_u32 v141, v140, 2, v57
	v_add_u32_e32 v129, v57, v204
	s_waitcnt lgkmcnt(1)
	v_mfma_f32_32x32x16_bf16 v[32:47], v[0:3], v[72:75], v[32:47]
	v_or_b32_e32 v0, 0x80, v204
	v_bitop3_b32 v0, v0, v8, v9 bitop3:0xde
	v_add_u32_e32 v150, 0, v0
	ds_read_b128 v[0:3], v150 offset:32768
	s_waitcnt lgkmcnt(1)
	v_mfma_f32_32x32x16_bf16 v[16:31], v[4:7], v[72:75], v[16:31]
	v_lshlrev_b32_e32 v5, 1, v52
	v_and_or_b32 v4, v10, 24, v11
	v_and_b32_e32 v5, 32, v5
	v_and_b32_e32 v6, 0x100, v10
	v_or3_b32 v58, v4, v5, v6
	ds_read_b128 v[4:7], v150 offset:40960
	v_add_u32_e32 v144, s25, v58
	s_waitcnt lgkmcnt(1)
	v_mfma_f32_32x32x16_bf16 v[32:47], v[0:3], v[68:71], v[32:47]
	v_or_b32_e32 v0, 0xa0, v204
	v_bitop3_b32 v0, v0, v8, v9 bitop3:0xde
	v_add_u32_e32 v153, 0, v0
	ds_read_b128 v[0:3], v153 offset:32768
	ds_read_b128 v[52:55], v153 offset:40960
	v_writelane_b32 v255, s12, 19
	s_waitcnt lgkmcnt(2)
	v_mfma_f32_32x32x16_bf16 v[16:31], v[4:7], v[68:71], v[16:31]
	v_writelane_b32 v255, s13, 20
	v_writelane_b32 v255, s14, 21
	v_writelane_b32 v255, s15, 22
	v_writelane_b32 v255, s16, 23
	v_writelane_b32 v255, s17, 24
	v_writelane_b32 v255, s18, 25
	v_writelane_b32 v255, s19, 26
	s_waitcnt lgkmcnt(1)
	v_mfma_f32_32x32x16_bf16 v[32:47], v[0:3], v[64:67], v[32:47]
	v_mov_b64_e32 v[0:1], s[76:77]
	v_mov_b64_e32 v[2:3], s[78:79]
	v_mov_b64_e32 v[4:5], s[80:81]
	v_mov_b64_e32 v[6:7], s[82:83]
	v_mov_b64_e32 v[8:9], s[84:85]
	v_mov_b64_e32 v[10:11], s[86:87]
	v_mov_b64_e32 v[12:13], s[88:89]
	s_waitcnt lgkmcnt(0)
	v_mfma_f32_32x32x16_bf16 v[16:31], v[52:55], v[64:67], v[16:31]
	s_nop 2
	v_max_f32_e32 v52, v33, v33
	v_max_f32_e32 v53, v32, v32
	v_max_f32_e32 v52, v53, v52
	v_max3_f32 v52, v52, v34, v35
	v_max3_f32 v52, v52, v36, v37
	v_max3_f32 v52, v52, v38, v39
	v_max3_f32 v52, v52, v40, v41
	v_max3_f32 v52, v52, v42, v43
	v_max3_f32 v52, v52, v44, v45
	v_max3_f32 v52, v52, v46, v47
	v_max3_f32 v52, v52, v16, v17
	v_max3_f32 v52, v52, v18, v19
	v_max3_f32 v52, v52, v20, v21
	v_max3_f32 v52, v52, v22, v23
	v_max3_f32 v52, v52, v24, v25
	v_max3_f32 v52, v52, v26, v27
	v_max3_f32 v52, v52, v28, v29
	v_max3_f32 v52, v52, v30, v31
	v_mov_b32_e32 v53, v52
	s_nop 1
	v_permlane32_swap_b32_e32 v52, v53
	v_max_f32_e32 v53, v53, v53
	v_max_f32_e32 v52, v52, v52
	v_max_f32_e32 v52, v52, v53
	v_mov_b64_e32 v[14:15], s[90:91]
	s_mov_b32 s80, 0x429cc470
	v_add_f32_e32 v53, 0x7149f2ca, v52
	v_cmp_ge_f32_e32 vcc, s80, v53
	s_cmp_eq_u64 vcc, exec
	v_max_f32_e32 v49, 0xf149f2ca, v52
	s_cselect_b64 vcc, -1, 0
	v_cndmask_b32_e32 v116, v49, v248, vcc
	v_mul_f32_e32 v48, 0xbe16c740, v116
	v_fmamk_f32 v32, v32, 0x3e16c740, v48
	v_exp_f32_e32 v126, v32
	v_fmamk_f32 v32, v33, 0x3e16c740, v48
	v_exp_f32_e32 v160, v32
	v_fmamk_f32 v32, v34, 0x3e16c740, v48
	v_exp_f32_e32 v127, v32
	v_fmamk_f32 v32, v35, 0x3e16c740, v48
	v_exp_f32_e32 v161, v32
	v_fmamk_f32 v32, v36, 0x3e16c740, v48
	v_exp_f32_e32 v158, v32
	v_fmamk_f32 v32, v37, 0x3e16c740, v48
	v_exp_f32_e32 v162, v32
	v_fmamk_f32 v32, v38, 0x3e16c740, v48
	v_exp_f32_e32 v159, v32
	v_fmamk_f32 v32, v39, 0x3e16c740, v48
	v_writelane_b32 v255, s20, 27
	v_exp_f32_e32 v163, v32
	v_fmamk_f32 v32, v40, 0x3e16c740, v48
	v_writelane_b32 v255, s21, 28
	v_exp_f32_e32 v118, v32
	v_fmamk_f32 v32, v41, 0x3e16c740, v48
	v_writelane_b32 v255, s22, 29
	v_exp_f32_e32 v121, v32
	v_fmamk_f32 v32, v42, 0x3e16c740, v48
	v_sub_f32_e32 v33, 0xf149f2ca, v49
	v_writelane_b32 v255, s23, 30
	v_exp_f32_e32 v119, v32
	v_fmamk_f32 v32, v43, 0x3e16c740, v48
	v_mul_f32_e32 v33, 0x3e16c740, v33
	v_writelane_b32 v255, s24, 31
	v_exp_f32_e32 v122, v32
	v_fmamk_f32 v32, v44, 0x3e16c740, v48
	v_exp_f32_e32 v33, v33
	v_writelane_b32 v255, s25, 32
	v_exp_f32_e32 v120, v32
	v_fmamk_f32 v32, v45, 0x3e16c740, v48
	v_writelane_b32 v255, s26, 33
	v_exp_f32_e32 v123, v32
	v_fmamk_f32 v32, v46, 0x3e16c740, v48
	v_writelane_b32 v255, s27, 34
	v_exp_f32_e32 v124, v32
	v_fmamk_f32 v32, v47, 0x3e16c740, v48
	v_pk_fma_f32 v[100:101], v[30:31], s[40:41], v[48:49] op_sel_hi:[1,0,0]
	v_pk_fma_f32 v[106:107], v[28:29], s[40:41], v[48:49] op_sel_hi:[1,0,0]
	v_pk_fma_f32 v[110:111], v[26:27], s[40:41], v[48:49] op_sel_hi:[1,0,0]
	v_pk_fma_f32 v[102:103], v[24:25], s[40:41], v[48:49] op_sel_hi:[1,0,0]
	v_pk_fma_f32 v[104:105], v[22:23], s[40:41], v[48:49] op_sel_hi:[1,0,0]
	v_pk_fma_f32 v[108:109], v[20:21], s[40:41], v[48:49] op_sel_hi:[1,0,0]
	v_pk_fma_f32 v[112:113], v[18:19], s[40:41], v[48:49] op_sel_hi:[1,0,0]
	v_pk_fma_f32 v[114:115], v[16:17], s[40:41], v[48:49] op_sel_hi:[1,0,0]
	s_addk_i32 s25, 0x4000
	v_mov_b64_e32 v[30:31], v[14:15]
	s_mov_b64 s[84:85], 0x90000
	s_movk_i32 s83, 0x6000
	s_movk_i32 s82, 0x100
	v_readlane_b32 s89, v255, 47
	v_readlane_b32 s76, v255, 37
	s_movk_i32 s90, 0x1fff
	s_mov_b32 s88, 0x42800000
	s_movk_i32 s87, 0x7000
	s_movk_i32 s86, 0x1200
	s_movk_i32 s81, 0x5000
	s_movk_i32 s78, 0x4000
	v_exp_f32_e32 v125, v32
	v_cndmask_b32_e64 v154, v33, 1.0, vcc
	v_add_u32_e32 v143, s25, v58
	v_mov_b64_e32 v[28:29], v[12:13]
	v_mov_b64_e32 v[26:27], v[10:11]
	v_mov_b64_e32 v[24:25], v[8:9]
	v_mov_b64_e32 v[22:23], v[6:7]
	v_mov_b64_e32 v[20:21], v[4:5]
	v_mov_b64_e32 v[18:19], v[2:3]
	v_mov_b64_e32 v[16:17], v[0:1]
	s_barrier
; #define SBAR() __builtin_amdgcn_sched_barrier(0)
; #define SLOAD(i, j) do { const long kr_ = KROW(j); sr_[i].vs0 = ld8(Vp + (kr_ + sr) * ldv + sc); sr_[i].ks0 = ld8(Kp + (kr_ + sr) * ldk + sc); \
;     if (DQK == 96) sr_[i].ks1 = ld8(Kp + (kr_ + sr2) * ldk + sc2); } while (0)
; #define SWRITE(b, i) do { *(bf16x8*)(V_lds + (b) * SHM_V + vst0) = sr_[i].vs0; *(bf16x8*)(K_lds + (b) * SHM_K + kst0) = sr_[i].ks0; \
;     if (DQK == 96) *(bf16x8*)(K_lds + (b) * SHM_K + kst1) = sr_[i].ks1; } while (0)
; #define RESC(a) do { if (__any((a) < 1.f)) { if (hi == 0) al_l[r32] = (a); asm volatile("s_waitcnt lgkmcnt(0)" ::: "memory"); \
;     _Pragma("unroll") for (int d = 0; d < 2; ++d) _Pragma("unroll") for (int r = 0; r < 16; ++r) o[d][r] *= al_l[crow(r, hi)]; } } while (0)
; #define BIAS(P0, P1, j) do { if (MODE == 1) { SBAR(); if ((j) >= nA) na_bias(P0, P1, na, rs0 + (j) - nA, hi); SBAR(); } } while (0)
; __device__ __forceinline__ void finishSM(f32x16& p0, f32x16& p1, float alpha, float& l_reg, bf16x8& pa0, bf16x8& pa1, bf16x8& pa2, bf16x8& pa3) {
; #pragma unroll
;   for (int r = 0; r < 16; ++r) p1[r] = __builtin_amdgcn_exp2f(p1[r]);
;   float ps = 0;
; #pragma unroll
;   for (int r = 0; r < 16; ++r) ps += p0[r];
; #pragma unroll
;   for (int r = 0; r < 16; ++r) ps += p1[r];
;   { auto rr = __builtin_amdgcn_permlane32_swap(__float_as_uint(ps), __float_as_uint(ps), false, false);
;     ps = __uint_as_float(rr[0]) + __uint_as_float(rr[1]); }
;   l_reg = l_reg * alpha + ps;
;     ...
;   PK4(p0, 0, pa0); PK4(p0, 8, pa1); PK4(p1, 0, pa2); PK4(p1, 8, pa3);
;     ...
; }
; template <int DQK, int MODE, int ldq, int ldk, int ldv> ...
;     ...
;   for (int j = 1; j + 1 < NT; j += 2) {
;     SBAR(); qkt<DQK>(pB0, pB1, K_lds + SHM_K, qr, r32, hi);
;     finishSM(pA0, pA1, alA, l_reg, pa0, pa1, pa2, pa3); SBAR();
;     SLOAD(SO, j + 2); SBAR();
;     pv_d0(o, vb0, pa0, pa1, pa2, pa3); BIAS(pB0, pB1, j); partialSM<DQK>(pB0, pB1, m_reg, mnB, alB);
;     __syncthreads(); SWRITE(0, SE);
;     RESC(alB); __syncthreads();
.LBB0_300:
	s_add_i32 s25, s11, -3
	s_cmp_lg_u32 s32, 0
	s_cbranch_scc1 .Lmy_h1B
	ds_read_b128 v[32:35], v148 offset:49152
	ds_read_b128 v[36:39], v148 offset:57344
	ds_read_b128 v[164:167], v152 offset:49152
	ds_read_b128 v[168:171], v152 offset:57344
	v_exp_f32_e32 v117, v114
	v_exp_f32_e32 v157, v115
	s_waitcnt lgkmcnt(3)
	v_mfma_f32_32x32x16_bf16 v[48:63], v[32:35], v[84:87], 0
	v_exp_f32_e32 v108, v108
	v_exp_f32_e32 v109, v109
	v_exp_f32_e32 v104, v104
	v_exp_f32_e32 v105, v105
	v_exp_f32_e32 v102, v102
	v_exp_f32_e32 v103, v103
	v_exp_f32_e32 v110, v110
	s_waitcnt lgkmcnt(2)
	v_mfma_f32_32x32x16_bf16 v[32:47], v[36:39], v[84:87], 0
	v_exp_f32_e32 v111, v111
	v_exp_f32_e32 v106, v106
	v_exp_f32_e32 v107, v107
	v_exp_f32_e32 v100, v100
	v_exp_f32_e32 v101, v101
	s_waitcnt lgkmcnt(1)
	v_mfma_f32_32x32x16_bf16 v[48:63], v[164:167], v[80:83], v[48:63]
	s_waitcnt lgkmcnt(0)
	v_mfma_f32_32x32x16_bf16 v[32:47], v[168:171], v[80:83], v[32:47]
	ds_read_b128 v[164:167], v151 offset:49152
	ds_read_b128 v[168:171], v151 offset:57344
	s_waitcnt lgkmcnt(1)
	v_mfma_f32_32x32x16_bf16 v[48:63], v[164:167], v[76:79], v[48:63]
	s_waitcnt lgkmcnt(0)
	v_mfma_f32_32x32x16_bf16 v[32:47], v[168:171], v[76:79], v[32:47]
	ds_read_b128 v[164:167], v149 offset:49152
	ds_read_b128 v[168:171], v149 offset:57344
	s_waitcnt lgkmcnt(1)
	v_mfma_f32_32x32x16_bf16 v[48:63], v[164:167], v[72:75], v[48:63]
	s_waitcnt lgkmcnt(0)
	v_mfma_f32_32x32x16_bf16 v[32:47], v[168:171], v[72:75], v[32:47]
	ds_read_b128 v[164:167], v150 offset:49152
	ds_read_b128 v[168:171], v150 offset:57344
	s_waitcnt lgkmcnt(1)
	v_mfma_f32_32x32x16_bf16 v[48:63], v[164:167], v[68:71], v[48:63]
	s_waitcnt lgkmcnt(0)
	v_mfma_f32_32x32x16_bf16 v[32:47], v[168:171], v[68:71], v[32:47]
	ds_read_b128 v[164:167], v153 offset:49152
	ds_read_b128 v[168:171], v153 offset:57344
	s_waitcnt vmcnt(0)
	ds_write_b128 v146, v[88:91] offset:32768
	ds_write_b128 v147, v[96:99] offset:32768
	ds_write_b128 v145, v[92:95] offset:16384
	s_waitcnt lgkmcnt(4)
	v_mfma_f32_32x32x16_bf16 v[48:63], v[164:167], v[64:67], v[48:63]
	v_exp_f32_e32 v164, v112
	v_add_f32_e32 v112, 0, v126
	v_add_f32_e32 v112, v160, v112
	v_add_f32_e32 v112, v127, v112
	v_add_f32_e32 v112, v161, v112
	v_add_f32_e32 v112, v158, v112
	v_add_f32_e32 v112, v162, v112
	v_add_f32_e32 v112, v159, v112
	v_add_f32_e32 v112, v163, v112
	v_add_f32_e32 v112, v118, v112
	v_add_f32_e32 v112, v121, v112
	v_add_f32_e32 v112, v119, v112
	v_add_f32_e32 v112, v122, v112
	v_add_f32_e32 v112, v120, v112
	v_add_f32_e32 v112, v123, v112
	v_add_f32_e32 v112, v124, v112
	v_exp_f32_e32 v165, v113
	v_add_f32_e32 v112, v125, v112
	v_add_f32_e32 v112, v117, v112
	v_add_f32_e32 v112, v157, v112
	v_add_f32_e32 v112, v164, v112
	v_add_f32_e32 v112, v165, v112
	v_add_f32_e32 v112, v108, v112
	v_add_f32_e32 v112, v109, v112
	v_add_f32_e32 v112, v104, v112
	v_add_f32_e32 v112, v105, v112
	v_add_f32_e32 v112, v102, v112
	v_add_f32_e32 v112, v103, v112
	s_waitcnt lgkmcnt(3)
	v_mfma_f32_32x32x16_bf16 v[32:47], v[168:171], v[64:67], v[32:47]
	ds_read_b64_tr_b16 v[192:193], v144 offset:0
	ds_read_b64_tr_b16 v[194:195], v144 offset:0x800
	ds_read_b64_tr_b16 v[196:197], v144 offset:0x1000
	ds_read_b64_tr_b16 v[198:199], v144 offset:0x1800
	ds_read_b64_tr_b16 v[200:201], v144 offset:0x2000
	ds_read_b64_tr_b16 v[202:203], v144 offset:0x2800
	ds_read_b64_tr_b16 v[210:211], v144 offset:0x3000
	ds_read_b64_tr_b16 v[212:213], v144 offset:0x3800
	v_add_f32_e32 v112, v110, v112
	v_add_f32_e32 v112, v111, v112
	v_add_f32_e32 v112, v106, v112
	v_add_f32_e32 v112, v107, v112
	v_add_f32_e32 v112, v100, v112
	v_add_f32_e32 v155, v101, v112
	v_mov_b32_e32 v156, v155
	v_cvt_pk_bf16_f32 v214, v126, v160
	v_cvt_pk_bf16_f32 v215, v127, v161
	v_cvt_pk_bf16_f32 v216, v158, v162
	s_nop 1
	v_permlane32_swap_b32_e32 v155, v156
	v_cvt_pk_bf16_f32 v217, v159, v163
	v_permlane32_swap_b32_e32 v214, v216
	v_cvt_pk_bf16_f32 v218, v118, v121
	v_cvt_pk_bf16_f32 v219, v119, v122
	v_cvt_pk_bf16_f32 v220, v120, v123
	v_cvt_pk_bf16_f32 v221, v124, v125
	v_cvt_pk_bf16_f32 v222, v117, v157
	v_cvt_pk_bf16_f32 v223, v164, v165
	v_cvt_pk_bf16_f32 v224, v108, v109
	v_cvt_pk_bf16_f32 v225, v104, v105
	v_cvt_pk_bf16_f32 v226, v102, v103
	v_cvt_pk_bf16_f32 v227, v110, v111
	v_cvt_pk_bf16_f32 v228, v106, v107
	v_cvt_pk_bf16_f32 v229, v100, v101
	v_permlane32_swap_b32_e32 v215, v217
	v_permlane32_swap_b32_e32 v218, v220
	v_permlane32_swap_b32_e32 v219, v221
	v_permlane32_swap_b32_e32 v222, v224
	v_permlane32_swap_b32_e32 v223, v225
	v_permlane32_swap_b32_e32 v226, v228
	v_permlane32_swap_b32_e32 v227, v229
	s_cmpk_lt_u32 s25, 0x7e
	s_cselect_b32 s0, 0, 0xffffff80
	s_cselect_b32 s1, s10, s24
	s_add_i32 s0, s0, s11
	s_lshl_b32 s0, s0, 6
	s_add_i32 s0, s0, s1
	s_sub_i32 s0, s0, 64
	s_ashr_i32 s1, s0, 31
	s_cmpk_lt_u32 s25, 0x7f
	s_cselect_b32 s98, 0, 0xffffff80
	s_cselect_b32 s99, s10, s24
	s_add_i32 s98, s98, s11
	s_lshl_b32 s98, s98, 6
	s_add_i32 s98, s98, s99
	s_addk_i32 s98, 0xff80
	s_ashr_i32 s99, s98, 31
	v_lshl_add_u64 v[100:101], s[0:1], 0, v[130:131]
	v_lshl_add_u64 v[104:105], s[98:99], 0, v[130:131]
	v_lshlrev_b64 v[104:105], 9, v[104:105]
	v_lshl_add_u64 v[104:105], v[134:135], 0, v[104:105]
	v_mad_u64_u32 v[102:103], s[12:13], v100, s70, v[136:137]
	v_or_b32_e32 v106, s0, v132
	v_mad_i32_i24 v103, v101, s70, v103
	v_mad_i64_i32 v[106:107], s[0:1], v106, s70, v[138:139]
	global_load_dwordx4 v[184:187], v[102:103], off
	s_nop 0
	global_load_dwordx4 v[188:191], v[104:105], off
	s_nop 0
	global_load_dwordx4 v[230:233], v[106:107], off offset:128
	s_waitcnt lgkmcnt(0)
; #define SBAR() __builtin_amdgcn_sched_barrier(0)
; template <int DQK> __device__ __forceinline__ void partialSM(f32x16& p0, f32x16& p1, float& m_reg, float& mn, float& alpha) {
;   constexpr float SCALE = (DQK == 96) ? 0.10206207261596577f : 0.125f;
;   constexpr float C = SCALE * 1.4426950408889634f;
;   float pmax = p0[0];
; #pragma unroll
;   for (int r = 1; r < 16; ++r) pmax = fmaxf(pmax, p0[r]);
; #pragma unroll
;   for (int r = 0; r < 16; ++r) pmax = fmaxf(pmax, p1[r]);
;   { auto rr = __builtin_amdgcn_permlane32_swap(__float_as_uint(pmax), __float_as_uint(pmax), false, false);
;     pmax = fmaxf(__uint_as_float(rr[0]), __uint_as_float(rr[1])); }
;   if (__builtin_expect(__all(pmax - m_reg <= THR / SCALE), 1)) { mn = m_reg; alpha = 1.f; }
;   else { mn = fmaxf(m_reg, pmax); alpha = __builtin_amdgcn_exp2f((m_reg - mn) * C); m_reg = mn; }
;   float mnC = -mn * C;
; #pragma unroll
;   for (int r = 0; r < 16; ++r) p0[r] = fmaf(p0[r], C, mnC);
; #pragma unroll
;   for (int r = 0; r < 16; ++r) p1[r] = fmaf(p1[r], C, mnC);
; #pragma unroll
;   for (int r = 0; r < 16; ++r) p0[r] = __builtin_amdgcn_exp2f(p0[r]);
; }
; template <int D0> __device__ __forceinline__ void pv_one(f32x16& od, int vb, bf16x8 pa0, bf16x8 pa1, bf16x8 pa2, bf16x8 pa3) {
;   const s16x4 l0 = tr_read<v_rd_off(D0, 0, 0)>(vb), h0 = tr_read<v_rd_off(D0, 0, 1)>(vb), l1 = tr_read<v_rd_off(D0, 1, 0)>(vb), h1 = tr_read<v_rd_off(D0, 1, 1)>(vb);
;   const s16x4 l2 = tr_read<v_rd_off(D0, 2, 0)>(vb), h2 = tr_read<v_rd_off(D0, 2, 1)>(vb), l3 = tr_read<v_rd_off(D0, 3, 0)>(vb), h3 = tr_read<v_rd_off(D0, 3, 1)>(vb);
;   asm volatile("s_waitcnt lgkmcnt(0)" ::: "memory"); SBAR();
;   od = __builtin_amdgcn_mfma_f32_32x32x16_bf16(pa0, PKLH(l0, h0), od, 0, 0, 0);
;   od = __builtin_amdgcn_mfma_f32_32x32x16_bf16(pa1, PKLH(l1, h1), od, 0, 0, 0);
;   od = __builtin_amdgcn_mfma_f32_32x32x16_bf16(pa2, PKLH(l2, h2), od, 0, 0, 0);
;   od = __builtin_amdgcn_mfma_f32_32x32x16_bf16(pa3, PKLH(l3, h3), od, 0, 0, 0);
; }
; __device__ __forceinline__ void pv_d0(f32x16* o, int vb, bf16x8 pa0, bf16x8 pa1, bf16x8 pa2, bf16x8 pa3) {
;   pv_one<0>(o[0], vb, pa0, pa1, pa2, pa3); pv_one<1>(o[1], vb, pa0, pa1, pa2, pa3);
; }
	s_nop 0
	v_mfma_f32_32x32x16_bf16 v[0:15], v[214:217], v[192:195], v[0:15]
	ds_read_b64_tr_b16 v[192:193], v144 offset:0x200
	ds_read_b64_tr_b16 v[194:195], v144 offset:0xa00
	v_max_f32_e32 v112, v49, v49
	v_max_f32_e32 v113, v48, v48
	v_max_f32_e32 v112, v113, v112
	v_max3_f32 v112, v112, v50, v51
	v_max3_f32 v112, v112, v52, v53
	v_mfma_f32_32x32x16_bf16 v[0:15], v[218:221], v[196:199], v[0:15]
	ds_read_b64_tr_b16 v[196:197], v144 offset:0x1200
	ds_read_b64_tr_b16 v[198:199], v144 offset:0x1a00
	v_max3_f32 v112, v112, v54, v55
	v_max3_f32 v112, v112, v56, v57
	v_max3_f32 v112, v112, v58, v59
	v_max3_f32 v112, v112, v60, v61
	v_max3_f32 v112, v112, v62, v63
	v_mfma_f32_32x32x16_bf16 v[0:15], v[222:225], v[200:203], v[0:15]
	ds_read_b64_tr_b16 v[200:201], v144 offset:0x2200
	ds_read_b64_tr_b16 v[202:203], v144 offset:0x2a00
	v_max3_f32 v112, v112, v32, v33
	v_max3_f32 v112, v112, v34, v35
	v_max3_f32 v112, v112, v36, v37
	v_max3_f32 v112, v112, v38, v39
	v_max3_f32 v112, v112, v40, v41
	v_mfma_f32_32x32x16_bf16 v[0:15], v[226:229], v[210:213], v[0:15]
	ds_read_b64_tr_b16 v[210:211], v144 offset:0x3200
	ds_read_b64_tr_b16 v[212:213], v144 offset:0x3a00
	v_max3_f32 v112, v112, v42, v43
	v_max3_f32 v112, v112, v44, v45
	v_max3_f32 v112, v112, v46, v47
	v_mov_b32_e32 v113, v112
	s_nop 1
	v_permlane32_swap_b32_e32 v112, v113
	v_max_f32_e32 v113, v113, v113
	v_max_f32_e32 v112, v112, v112
	v_max_f32_e32 v112, v112, v113
	v_sub_f32_e32 v113, v112, v116
	v_cmp_ge_f32_e32 vcc, s80, v113
	v_max_f32_e32 v113, v116, v116
	v_max_f32_e32 v112, v113, v112
	s_waitcnt lgkmcnt(0)
	v_mfma_f32_32x32x16_bf16 v[16:31], v[214:217], v[192:195], v[16:31]
	v_sub_f32_e32 v113, v116, v112
	v_mul_f32_e32 v113, 0x3e16c740, v113
	v_exp_f32_e32 v113, v113
	s_cmp_eq_u64 vcc, exec
	s_cselect_b64 s[0:1], -1, 0
	v_cndmask_b32_e64 v157, v113, 1.0, s[0:1]
	v_cmp_gt_f32_e32 vcc, 1.0, v157
	v_cndmask_b32_e64 v158, v112, v116, s[0:1]
	v_mul_f32_e32 v159, 0xbe16c740, v158
	v_fmamk_f32 v48, v48, 0x3e16c740, v159
	v_fmamk_f32 v49, v49, 0x3e16c740, v159
	v_fmamk_f32 v50, v50, 0x3e16c740, v159
	v_fmamk_f32 v51, v51, 0x3e16c740, v159
	v_mfma_f32_32x32x16_bf16 v[16:31], v[218:221], v[196:199], v[16:31]
	v_fmamk_f32 v52, v52, 0x3e16c740, v159
	v_fmamk_f32 v53, v53, 0x3e16c740, v159
	v_fmamk_f32 v54, v54, 0x3e16c740, v159
	v_fmamk_f32 v55, v55, 0x3e16c740, v159
	v_fmamk_f32 v56, v56, 0x3e16c740, v159
	v_fmamk_f32 v57, v57, 0x3e16c740, v159
	v_fmamk_f32 v58, v58, 0x3e16c740, v159
	v_fmamk_f32 v59, v59, 0x3e16c740, v159
	v_fmamk_f32 v60, v60, 0x3e16c740, v159
	v_fmamk_f32 v61, v61, 0x3e16c740, v159
	v_mfma_f32_32x32x16_bf16 v[16:31], v[222:225], v[200:203], v[16:31]
	v_fmamk_f32 v62, v62, 0x3e16c740, v159
	v_fmamk_f32 v63, v63, 0x3e16c740, v159
	v_exp_f32_e32 v112, v48
	v_exp_f32_e32 v127, v49
	v_exp_f32_e32 v113, v50
	v_exp_f32_e32 v126, v51
	v_exp_f32_e32 v114, v52
	v_exp_f32_e32 v125, v53
	v_exp_f32_e32 v115, v54
	v_exp_f32_e32 v124, v55
	v_mfma_f32_32x32x16_bf16 v[16:31], v[226:229], v[210:213], v[16:31]
	v_exp_f32_e32 v116, v56
	v_exp_f32_e32 v123, v57
	v_exp_f32_e32 v117, v58
	v_exp_f32_e32 v122, v59
	v_exp_f32_e32 v118, v60
	v_exp_f32_e32 v121, v61
	v_exp_f32_e32 v119, v62
	v_exp_f32_e32 v120, v63
	v_fmamk_f32 v164, v42, 0x3e16c740, v159
	v_fmamk_f32 v165, v43, 0x3e16c740, v159
	v_fmamk_f32 v167, v32, 0x3e16c740, v159
	v_fmamk_f32 v168, v33, 0x3e16c740, v159
	v_fmamk_f32 v169, v34, 0x3e16c740, v159
	v_fmamk_f32 v170, v35, 0x3e16c740, v159
	v_fmamk_f32 v171, v36, 0x3e16c740, v159
	v_fmamk_f32 v172, v37, 0x3e16c740, v159
	v_fmamk_f32 v160, v38, 0x3e16c740, v159
	v_fmamk_f32 v161, v39, 0x3e16c740, v159
	v_fmamk_f32 v162, v40, 0x3e16c740, v159
	v_fmamk_f32 v163, v41, 0x3e16c740, v159
	v_fmamk_f32 v166, v44, 0x3e16c740, v159
	v_fmamk_f32 v173, v45, 0x3e16c740, v159
	v_fmamk_f32 v174, v46, 0x3e16c740, v159
	v_fmac_f32_e32 v159, 0x3e16c740, v47
	s_cbranch_vccz .LBB0_304
	s_and_saveexec_b64 s[12:13], s[4:5]
	ds_write_b32 v141, v157 offset:128
	s_or_b64 exec, exec, s[12:13]
	s_waitcnt lgkmcnt(0)
	ds_read_b128 v[192:195], v129 offset:224
	ds_read_b128 v[196:199], v129 offset:192
	ds_read_b128 v[200:203], v129 offset:160
	ds_read_b128 v[210:213], v129 offset:128
	s_waitcnt lgkmcnt(3)
	v_pk_mul_f32 v[14:15], v[14:15], v[194:195]
	s_waitcnt lgkmcnt(2)
	v_pk_mul_f32 v[10:11], v[10:11], v[198:199]
	s_waitcnt lgkmcnt(1)
	v_pk_mul_f32 v[6:7], v[6:7], v[202:203]
	s_waitcnt lgkmcnt(0)
	v_pk_mul_f32 v[2:3], v[2:3], v[212:213]
	v_pk_mul_f32 v[12:13], v[12:13], v[192:193]
	v_pk_mul_f32 v[8:9], v[8:9], v[196:197]
	v_pk_mul_f32 v[4:5], v[4:5], v[200:201]
	v_pk_mul_f32 v[0:1], v[0:1], v[210:211]
	v_pk_mul_f32 v[30:31], v[30:31], v[194:195]
	v_pk_mul_f32 v[26:27], v[26:27], v[198:199]
	v_pk_mul_f32 v[22:23], v[22:23], v[202:203]
	v_pk_mul_f32 v[18:19], v[18:19], v[212:213]
	v_pk_mul_f32 v[28:29], v[28:29], v[192:193]
	v_pk_mul_f32 v[24:25], v[24:25], v[196:197]
	v_pk_mul_f32 v[20:21], v[20:21], v[200:201]
	v_pk_mul_f32 v[16:17], v[16:17], v[210:211]
; #define SBAR() __builtin_amdgcn_sched_barrier(0)
; #define SLOAD(i, j) do { const long kr_ = KROW(j); sr_[i].vs0 = ld8(Vp + (kr_ + sr) * ldv + sc); sr_[i].ks0 = ld8(Kp + (kr_ + sr) * ldk + sc); \
;     if (DQK == 96) sr_[i].ks1 = ld8(Kp + (kr_ + sr2) * ldk + sc2); } while (0)
; __device__ __forceinline__ void finishSM(f32x16& p0, f32x16& p1, float alpha, float& l_reg, bf16x8& pa0, bf16x8& pa1, bf16x8& pa2, bf16x8& pa3) {
; #pragma unroll
;   for (int r = 0; r < 16; ++r) p1[r] = __builtin_amdgcn_exp2f(p1[r]);
;   float ps = 0;
; #pragma unroll
;   for (int r = 0; r < 16; ++r) ps += p0[r];
; #pragma unroll
;   for (int r = 0; r < 16; ++r) ps += p1[r];
;   { auto rr = __builtin_amdgcn_permlane32_swap(__float_as_uint(ps), __float_as_uint(ps), false, false);
;     ps = __uint_as_float(rr[0]) + __uint_as_float(rr[1]); }
;   l_reg = l_reg * alpha + ps;
;     ...
;   PK4(p0, 0, pa0); PK4(p0, 8, pa1); PK4(p1, 0, pa2); PK4(p1, 8, pa3);
;     ...
; }
; template <int DQK, int MODE, int ldq, int ldk, int ldv> ...
;     ...
;     SBAR(); qkt<DQK>(pA0, pA1, K_lds, qr, r32, hi);
;     finishSM(pB0, pB1, alB, l_reg, pa0, pa1, pa2, pa3); SBAR();
;     if (j + 3 < NT) SLOAD(SE, j + 3); SBAR();
.LBB0_304:
	s_waitcnt lgkmcnt(0)
	s_barrier
	ds_read_b128 v[32:35], v148 offset:32768
	ds_read_b128 v[36:39], v148 offset:40960
	ds_read_b128 v[176:179], v152 offset:32768
	ds_read_b128 v[180:183], v152 offset:40960
	v_exp_f32_e32 v175, v164
	v_add_f32_e32 v164, 0, v112
	s_waitcnt lgkmcnt(3)
	v_mfma_f32_32x32x16_bf16 v[48:63], v[32:35], v[84:87], 0
	v_add_f32_e32 v164, v127, v164
	v_add_f32_e32 v164, v113, v164
	v_add_f32_e32 v164, v126, v164
	v_add_f32_e32 v164, v114, v164
	v_add_f32_e32 v164, v125, v164
	v_add_f32_e32 v164, v115, v164
	v_add_f32_e32 v164, v124, v164
	s_waitcnt lgkmcnt(2)
	v_mfma_f32_32x32x16_bf16 v[32:47], v[36:39], v[84:87], 0
	v_add_f32_e32 v164, v116, v164
	v_add_f32_e32 v164, v123, v164
	v_add_f32_e32 v164, v117, v164
	v_add_f32_e32 v164, v122, v164
	v_exp_f32_e32 v167, v167
	v_add_f32_e32 v164, v118, v164
	v_exp_f32_e32 v168, v168
	s_waitcnt lgkmcnt(1)
	v_mfma_f32_32x32x16_bf16 v[48:63], v[176:179], v[80:83], v[48:63]
	v_add_f32_e32 v164, v121, v164
	v_exp_f32_e32 v169, v169
	v_add_f32_e32 v164, v119, v164
	v_exp_f32_e32 v170, v170
	v_add_f32_e32 v164, v120, v164
	v_exp_f32_e32 v171, v171
	v_add_f32_e32 v164, v167, v164
	s_waitcnt lgkmcnt(0)
	v_mfma_f32_32x32x16_bf16 v[32:47], v[180:183], v[80:83], v[32:47]
	ds_read_b128 v[176:179], v151 offset:32768
	ds_read_b128 v[180:183], v151 offset:40960
	v_exp_f32_e32 v172, v172
	v_add_f32_e32 v164, v168, v164
	v_exp_f32_e32 v160, v160
	v_add_f32_e32 v164, v169, v164
	v_exp_f32_e32 v161, v161
	v_add_f32_e32 v164, v170, v164
	s_waitcnt lgkmcnt(1)
	v_mfma_f32_32x32x16_bf16 v[48:63], v[176:179], v[76:79], v[48:63]
	v_exp_f32_e32 v162, v162
	v_add_f32_e32 v164, v171, v164
	v_exp_f32_e32 v163, v163
	v_add_f32_e32 v164, v172, v164
	v_add_f32_e32 v164, v160, v164
	v_add_f32_e32 v164, v161, v164
	v_exp_f32_e32 v166, v166
	s_waitcnt lgkmcnt(0)
	v_mfma_f32_32x32x16_bf16 v[32:47], v[180:183], v[76:79], v[32:47]
	ds_read_b128 v[176:179], v149 offset:32768
	ds_read_b128 v[180:183], v149 offset:40960
	v_add_f32_e32 v164, v162, v164
	v_exp_f32_e32 v173, v173
	v_add_f32_e32 v164, v163, v164
	v_exp_f32_e32 v174, v174
	v_add_f32_e32 v164, v175, v164
	v_exp_f32_e32 v159, v159
	s_waitcnt lgkmcnt(1)
	v_mfma_f32_32x32x16_bf16 v[48:63], v[176:179], v[72:75], v[48:63]
	s_waitcnt lgkmcnt(0)
	v_mfma_f32_32x32x16_bf16 v[32:47], v[180:183], v[72:75], v[32:47]
	ds_read_b128 v[176:179], v150 offset:32768
	ds_read_b128 v[180:183], v150 offset:40960
	s_waitcnt lgkmcnt(1)
	v_mfma_f32_32x32x16_bf16 v[48:63], v[176:179], v[68:71], v[48:63]
	s_waitcnt lgkmcnt(0)
	v_mfma_f32_32x32x16_bf16 v[32:47], v[180:183], v[68:71], v[32:47]
	ds_read_b128 v[176:179], v153 offset:32768
	ds_read_b128 v[180:183], v153 offset:40960
	s_waitcnt vmcnt(0)
	ds_write_b128 v146, v[184:187] offset:49152
	ds_write_b128 v147, v[230:233] offset:49152
	ds_write_b128 v145, v[188:191]
	v_cvt_pk_bf16_f32 v214, v112, v127
	v_cvt_pk_bf16_f32 v215, v113, v126
	v_cvt_pk_bf16_f32 v216, v114, v125
	v_cvt_pk_bf16_f32 v217, v115, v124
	v_cvt_pk_bf16_f32 v218, v116, v123
	v_cvt_pk_bf16_f32 v219, v117, v122
	s_waitcnt lgkmcnt(4)
	v_mfma_f32_32x32x16_bf16 v[48:63], v[176:179], v[64:67], v[48:63]
	v_exp_f32_e32 v176, v165
	v_cvt_pk_bf16_f32 v220, v118, v121
	v_cvt_pk_bf16_f32 v221, v119, v120
	v_cvt_pk_bf16_f32 v222, v167, v168
	v_cvt_pk_bf16_f32 v223, v169, v170
	v_cvt_pk_bf16_f32 v224, v171, v172
	s_nop 0
	v_add_f32_e32 v164, v176, v164
	s_waitcnt lgkmcnt(3)
	v_mfma_f32_32x32x16_bf16 v[32:47], v[180:183], v[64:67], v[32:47]
	ds_read_b64_tr_b16 v[192:193], v143 offset:0
	ds_read_b64_tr_b16 v[194:195], v143 offset:0x800
	ds_read_b64_tr_b16 v[196:197], v143 offset:0x1000
	ds_read_b64_tr_b16 v[198:199], v143 offset:0x1800
	ds_read_b64_tr_b16 v[200:201], v143 offset:0x2000
	ds_read_b64_tr_b16 v[202:203], v143 offset:0x2800
	ds_read_b64_tr_b16 v[210:211], v143 offset:0x3000
	ds_read_b64_tr_b16 v[212:213], v143 offset:0x3800
	v_add_f32_e32 v164, v166, v164
	v_add_f32_e32 v164, v173, v164
	v_add_f32_e32 v164, v174, v164
	v_add_f32_e32 v164, v159, v164
	v_mov_b32_e32 v165, v164
	v_cvt_pk_bf16_f32 v225, v160, v161
	v_cvt_pk_bf16_f32 v226, v162, v163
	v_cvt_pk_bf16_f32 v227, v175, v176
	v_cvt_pk_bf16_f32 v228, v166, v173
	v_cvt_pk_bf16_f32 v229, v174, v159
	s_nop 1
	v_permlane32_swap_b32_e32 v164, v165
	v_permlane32_swap_b32_e32 v214, v216
	v_permlane32_swap_b32_e32 v215, v217
	v_permlane32_swap_b32_e32 v218, v220
	v_permlane32_swap_b32_e32 v219, v221
	v_permlane32_swap_b32_e32 v222, v224
	v_permlane32_swap_b32_e32 v223, v225
	v_permlane32_swap_b32_e32 v226, v228
	v_permlane32_swap_b32_e32 v227, v229
	s_cmpk_lt_u32 s25, 0x7e
	s_cselect_b32 s98, 0, 0xffffff80
	s_cselect_b32 s99, s10, s24
	s_add_i32 s98, s98, s11
	s_lshl_b32 s98, s98, 6
	s_add_i32 s98, s98, s99
	s_sub_i32 s98, s98, 64
	s_ashr_i32 s99, s98, 31
	v_lshl_add_u64 v[92:93], s[98:99], 0, v[130:131]
	v_lshlrev_b64 v[92:93], 9, v[92:93]
	v_lshl_add_u64 v[92:93], v[134:135], 0, v[92:93]
	global_load_dwordx4 v[92:95], v[92:93], off
	s_cmpk_gt_u32 s25, 0x80
	s_cbranch_scc1 .LBB0_306
	s_cmpk_lt_u32 s25, 0x7d
	s_cselect_b32 s0, 0, 0xffffff80
	s_cselect_b32 s1, s10, s24
	s_add_i32 s0, s0, s11
	s_lshl_b32 s0, s0, 6
	s_add_i32 s0, s0, s1
	s_ashr_i32 s1, s0, 31
	v_lshl_add_u64 v[88:89], s[0:1], 0, v[130:131]
	v_mad_u64_u32 v[90:91], s[12:13], v88, s70, v[136:137]
	v_or_b32_e32 v96, s0, v132
	v_mad_i32_i24 v91, v89, s70, v91
	v_mad_i64_i32 v[96:97], s[0:1], v96, s70, v[138:139]
	global_load_dwordx4 v[88:91], v[90:91], off
	s_nop 0
	s_nop 0
	global_load_dwordx4 v[96:99], v[96:97], off offset:128
; #define SWRITE(b, i) do { *(bf16x8*)(V_lds + (b) * SHM_V + vst0) = sr_[i].vs0; *(bf16x8*)(K_lds + (b) * SHM_K + kst0) = sr_[i].ks0; \
;     if (DQK == 96) *(bf16x8*)(K_lds + (b) * SHM_K + kst1) = sr_[i].ks1; } while (0)
; #define RESC(a) do { if (__any((a) < 1.f)) { if (hi == 0) al_l[r32] = (a); asm volatile("s_waitcnt lgkmcnt(0)" ::: "memory"); \
;     _Pragma("unroll") for (int d = 0; d < 2; ++d) _Pragma("unroll") for (int r = 0; r < 16; ++r) o[d][r] *= al_l[crow(r, hi)]; } } while (0)
; #define BIAS(P0, P1, j) do { if (MODE == 1) { SBAR(); if ((j) >= nA) na_bias(P0, P1, na, rs0 + (j) - nA, hi); SBAR(); } } while (0)
; template <int DQK> __device__ __forceinline__ void partialSM(f32x16& p0, f32x16& p1, float& m_reg, float& mn, float& alpha) {
;   constexpr float SCALE = (DQK == 96) ? 0.10206207261596577f : 0.125f;
;   constexpr float C = SCALE * 1.4426950408889634f;
;   float pmax = p0[0];
; #pragma unroll
;   for (int r = 1; r < 16; ++r) pmax = fmaxf(pmax, p0[r]);
; #pragma unroll
;   for (int r = 0; r < 16; ++r) pmax = fmaxf(pmax, p1[r]);
;   { auto rr = __builtin_amdgcn_permlane32_swap(__float_as_uint(pmax), __float_as_uint(pmax), false, false);
;     pmax = fmaxf(__uint_as_float(rr[0]), __uint_as_float(rr[1])); }
;   if (__builtin_expect(__all(pmax - m_reg <= THR / SCALE), 1)) { mn = m_reg; alpha = 1.f; }
;   else { mn = fmaxf(m_reg, pmax); alpha = __builtin_amdgcn_exp2f((m_reg - mn) * C); m_reg = mn; }
;   float mnC = -mn * C;
; #pragma unroll
;   for (int r = 0; r < 16; ++r) p0[r] = fmaf(p0[r], C, mnC);
; #pragma unroll
;   for (int r = 0; r < 16; ++r) p1[r] = fmaf(p1[r], C, mnC);
; #pragma unroll
;   for (int r = 0; r < 16; ++r) p0[r] = __builtin_amdgcn_exp2f(p0[r]);
; }
; template <int DQK, int MODE, int ldq, int ldk, int ldv> ...
;     ...
;     pv_d0(o, vb0 + (int)SHM_V, pa0, pa1, pa2, pa3); BIAS(pA0, pA1, j + 1); partialSM<DQK>(pA0, pA1, m_reg, mnA, alA);
;     __syncthreads(); SWRITE(1, SO);
;     RESC(alA); __syncthreads();
;   }
.LBB0_306:
	s_waitcnt lgkmcnt(0)
	s_nop 0
	v_mfma_f32_32x32x16_bf16 v[0:15], v[214:217], v[192:195], v[0:15]
	ds_read_b64_tr_b16 v[192:193], v143 offset:0x200
	ds_read_b64_tr_b16 v[194:195], v143 offset:0xa00
	v_max_f32_e32 v112, v49, v49
	v_max_f32_e32 v113, v48, v48
	v_max_f32_e32 v112, v113, v112
	v_max3_f32 v112, v112, v50, v51
	v_max3_f32 v112, v112, v52, v53
	v_mfma_f32_32x32x16_bf16 v[0:15], v[218:221], v[196:199], v[0:15]
	ds_read_b64_tr_b16 v[196:197], v143 offset:0x1200
	ds_read_b64_tr_b16 v[198:199], v143 offset:0x1a00
	v_max3_f32 v112, v112, v54, v55
	v_max3_f32 v112, v112, v56, v57
	v_max3_f32 v112, v112, v58, v59
	v_max3_f32 v112, v112, v60, v61
	v_max3_f32 v112, v112, v62, v63
	v_mfma_f32_32x32x16_bf16 v[0:15], v[222:225], v[200:203], v[0:15]
	ds_read_b64_tr_b16 v[200:201], v143 offset:0x2200
	ds_read_b64_tr_b16 v[202:203], v143 offset:0x2a00
	v_max3_f32 v112, v112, v32, v33
	v_max3_f32 v112, v112, v34, v35
	v_max3_f32 v112, v112, v36, v37
	v_max3_f32 v112, v112, v38, v39
	v_max3_f32 v112, v112, v40, v41
	v_mfma_f32_32x32x16_bf16 v[0:15], v[226:229], v[210:213], v[0:15]
	ds_read_b64_tr_b16 v[210:211], v143 offset:0x3200
	ds_read_b64_tr_b16 v[212:213], v143 offset:0x3a00
	v_max3_f32 v112, v112, v42, v43
	v_max3_f32 v112, v112, v44, v45
	v_max3_f32 v112, v112, v46, v47
	v_mov_b32_e32 v113, v112
	s_nop 1
	v_permlane32_swap_b32_e32 v112, v113
	v_max_f32_e32 v113, v113, v113
	v_max_f32_e32 v112, v112, v112
	v_max_f32_e32 v112, v112, v113
	v_sub_f32_e32 v113, v112, v158
	v_cmp_ge_f32_e32 vcc, s80, v113
	v_max_f32_e32 v113, v158, v158
	v_max_f32_e32 v112, v113, v112
	s_waitcnt lgkmcnt(0)
	v_mfma_f32_32x32x16_bf16 v[16:31], v[214:217], v[192:195], v[16:31]
	v_sub_f32_e32 v113, v158, v112
	v_mul_f32_e32 v113, 0x3e16c740, v113
	v_exp_f32_e32 v113, v113
	s_cmp_eq_u64 vcc, exec
	s_cselect_b64 s[0:1], -1, 0
	v_cndmask_b32_e64 v117, v113, 1.0, s[0:1]
	v_cmp_gt_f32_e32 vcc, 1.0, v117
	v_cndmask_b32_e64 v116, v112, v158, s[0:1]
	v_mul_f32_e32 v100, 0xbe16c740, v116
	v_mov_b32_e32 v101, v100
	v_fmamk_f32 v48, v48, 0x3e16c740, v100
	v_fmamk_f32 v49, v49, 0x3e16c740, v100
	v_fmamk_f32 v50, v50, 0x3e16c740, v100
	v_mfma_f32_32x32x16_bf16 v[16:31], v[218:221], v[196:199], v[16:31]
	v_fmamk_f32 v51, v51, 0x3e16c740, v100
	v_fmamk_f32 v52, v52, 0x3e16c740, v100
	v_fmamk_f32 v53, v53, 0x3e16c740, v100
	v_fmamk_f32 v54, v54, 0x3e16c740, v100
	v_fmamk_f32 v55, v55, 0x3e16c740, v100
	v_fmamk_f32 v56, v56, 0x3e16c740, v100
	v_fmamk_f32 v57, v57, 0x3e16c740, v100
	v_fmamk_f32 v58, v58, 0x3e16c740, v100
	v_fmamk_f32 v59, v59, 0x3e16c740, v100
	v_fmamk_f32 v60, v60, 0x3e16c740, v100
	v_mfma_f32_32x32x16_bf16 v[16:31], v[222:225], v[200:203], v[16:31]
	v_fmamk_f32 v61, v61, 0x3e16c740, v100
	v_fmamk_f32 v62, v62, 0x3e16c740, v100
	v_fmac_f32_e32 v101, 0x3e16c740, v63
	v_exp_f32_e32 v126, v48
	v_exp_f32_e32 v160, v49
	v_exp_f32_e32 v127, v50
	v_exp_f32_e32 v161, v51
	v_exp_f32_e32 v158, v52
	v_exp_f32_e32 v162, v53
	v_exp_f32_e32 v159, v54
	v_mfma_f32_32x32x16_bf16 v[16:31], v[226:229], v[210:213], v[16:31]
	v_exp_f32_e32 v163, v55
	v_exp_f32_e32 v118, v56
	v_exp_f32_e32 v121, v57
	v_exp_f32_e32 v119, v58
	v_exp_f32_e32 v122, v59
	v_exp_f32_e32 v120, v60
	v_exp_f32_e32 v123, v61
	v_exp_f32_e32 v124, v62
	v_exp_f32_e32 v125, v101
	v_pk_fma_f32 v[114:115], v[32:33], s[40:41], v[100:101] op_sel_hi:[1,0,0]
	v_add_f32_e32 v32, v155, v156
	v_fmac_f32_e32 v32, v154, v142
	v_add_f32_e32 v142, v164, v165
	v_pk_fma_f32 v[112:113], v[34:35], s[40:41], v[100:101] op_sel_hi:[1,0,0]
	v_pk_fma_f32 v[108:109], v[36:37], s[40:41], v[100:101] op_sel_hi:[1,0,0]
	v_pk_fma_f32 v[104:105], v[38:39], s[40:41], v[100:101] op_sel_hi:[1,0,0]
	v_pk_fma_f32 v[102:103], v[40:41], s[40:41], v[100:101] op_sel_hi:[1,0,0]
	v_pk_fma_f32 v[110:111], v[42:43], s[40:41], v[100:101] op_sel_hi:[1,0,0]
	v_pk_fma_f32 v[106:107], v[44:45], s[40:41], v[100:101] op_sel_hi:[1,0,0]
	v_pk_fma_f32 v[100:101], v[46:47], s[40:41], v[100:101] op_sel_hi:[1,0,0]
	v_fmac_f32_e32 v142, v32, v157
	s_cbranch_vccz .LBB0_310
	s_and_saveexec_b64 s[12:13], s[4:5]
	ds_write_b32 v141, v117 offset:128
	s_or_b64 exec, exec, s[12:13]
	s_waitcnt lgkmcnt(0)
	ds_read_b128 v[192:195], v129 offset:224
	ds_read_b128 v[196:199], v129 offset:192
	ds_read_b128 v[200:203], v129 offset:160
	ds_read_b128 v[210:213], v129 offset:128
	s_waitcnt lgkmcnt(3)
	v_pk_mul_f32 v[14:15], v[14:15], v[194:195]
	s_waitcnt lgkmcnt(2)
	v_pk_mul_f32 v[10:11], v[10:11], v[198:199]
	s_waitcnt lgkmcnt(1)
	v_pk_mul_f32 v[6:7], v[6:7], v[202:203]
	s_waitcnt lgkmcnt(0)
	v_pk_mul_f32 v[2:3], v[2:3], v[212:213]
	v_pk_mul_f32 v[12:13], v[12:13], v[192:193]
	v_pk_mul_f32 v[8:9], v[8:9], v[196:197]
	v_pk_mul_f32 v[4:5], v[4:5], v[200:201]
	v_pk_mul_f32 v[0:1], v[0:1], v[210:211]
	v_pk_mul_f32 v[30:31], v[30:31], v[194:195]
	v_pk_mul_f32 v[26:27], v[26:27], v[198:199]
	v_pk_mul_f32 v[22:23], v[22:23], v[202:203]
	v_pk_mul_f32 v[18:19], v[18:19], v[212:213]
	v_pk_mul_f32 v[28:29], v[28:29], v[192:193]
	v_pk_mul_f32 v[24:25], v[24:25], v[196:197]
	v_pk_mul_f32 v[20:21], v[20:21], v[200:201]
	v_pk_mul_f32 v[16:17], v[16:17], v[210:211]
.LBB0_310:
	s_add_i32 s11, s11, 2
	s_cmpk_gt_u32 s25, 0x80
	s_waitcnt lgkmcnt(0)
	s_barrier
	s_cbranch_scc1 .LBB0_312
	v_mov_b32_e32 v154, v117
	s_branch .LBB0_300
; #define SBAR() __builtin_amdgcn_sched_barrier(0)
; #define SLOAD(i, j) do { const long kr_ = KROW(j); sr_[i].vs0 = ld8(Vp + (kr_ + sr) * ldv + sc); sr_[i].ks0 = ld8(Kp + (kr_ + sr) * ldk + sc); \
;     if (DQK == 96) sr_[i].ks1 = ld8(Kp + (kr_ + sr2) * ldk + sc2); } while (0)
; #define SWRITE(b, i) do { *(bf16x8*)(V_lds + (b) * SHM_V + vst0) = sr_[i].vs0; *(bf16x8*)(K_lds + (b) * SHM_K + kst0) = sr_[i].ks0; \
;     if (DQK == 96) *(bf16x8*)(K_lds + (b) * SHM_K + kst1) = sr_[i].ks1; } while (0)
; #define BIAS(P0, P1, j) do { if (MODE == 1) { SBAR(); if ((j) >= nA) na_bias(P0, P1, na, rs0 + (j) - nA, hi); SBAR(); } } while (0)
; __device__ __forceinline__ void finishSM(f32x16& p0, f32x16& p1, float alpha, float& l_reg, bf16x8& pa0, bf16x8& pa1, bf16x8& pa2, bf16x8& pa3) {
; #pragma unroll
;   for (int r = 0; r < 16; ++r) p1[r] = __builtin_amdgcn_exp2f(p1[r]);
;   float ps = 0;
; #pragma unroll
;   for (int r = 0; r < 16; ++r) ps += p0[r];
; #pragma unroll
;   for (int r = 0; r < 16; ++r) ps += p1[r];
;   { auto rr = __builtin_amdgcn_permlane32_swap(__float_as_uint(ps), __float_as_uint(ps), false, false);
;     ps = __uint_as_float(rr[0]) + __uint_as_float(rr[1]); }
;   l_reg = l_reg * alpha + ps;
;     ...
;   PK4(p0, 0, pa0); PK4(p0, 8, pa1); PK4(p1, 0, pa2); PK4(p1, 8, pa3);
;     ...
; }
; template <int DQK> __device__ __forceinline__ void qkt(f32x16& p0, f32x16& p1, const char* Ks, const bf16x8* qr, int r32, int hi) {
;   p0 = f32x16{}; p1 = f32x16{};
; #pragma unroll
;   for (int d0 = 0; d0 < DQK / 16; ++d0) { int cb = (d0 * 16 + hi * 8) * 2;
;     bf16x8 b0 = *reinterpret_cast<const bf16x8*>(Ks + KSWZ(r32, cb));
;     bf16x8 b1 = *reinterpret_cast<const bf16x8*>(Ks + KSWZ(32 + r32, cb));
;     p0 = __builtin_amdgcn_mfma_f32_32x32x16_bf16(b0, qr[d0], p0, 0, 0, 0);
;     p1 = __builtin_amdgcn_mfma_f32_32x32x16_bf16(b1, qr[d0], p1, 0, 0, 0); }
; }
; template <int DQK, int MODE, int ldq, int ldk, int ldv> ...
;     ...
;     SBAR(); qkt<DQK>(pB0, pB1, K_lds + SHM_K, qr, r32, hi);
;     finishSM(pA0, pA1, alA, l_reg, pa0, pa1, pa2, pa3); SBAR();
;     SLOAD(SO, j + 2); SBAR();
;     pv_d0(o, vb0, pa0, pa1, pa2, pa3); BIAS(pB0, pB1, j); partialSM<DQK>(pB0, pB1, m_reg, mnB, alB);
;     __syncthreads(); SWRITE(0, SE);
.Lmy_h1B:
	s_waitcnt vmcnt(0)
	ds_write_b128 v146, v[88:91] offset:32768
	ds_write_b128 v147, v[96:99] offset:32768
	ds_write_b128 v145, v[92:95] offset:16384
	v_exp_f32_e32 v117, v114
	v_exp_f32_e32 v157, v115
	v_exp_f32_e32 v108, v108
	v_exp_f32_e32 v109, v109
	v_exp_f32_e32 v104, v104
	v_exp_f32_e32 v105, v105
	v_exp_f32_e32 v102, v102
	v_exp_f32_e32 v103, v103
	v_exp_f32_e32 v110, v110
	v_exp_f32_e32 v111, v111
	v_exp_f32_e32 v106, v106
	v_exp_f32_e32 v107, v107
	v_exp_f32_e32 v100, v100
	v_exp_f32_e32 v101, v101
	v_exp_f32_e32 v164, v112
	v_add_f32_e32 v112, 0, v126
	v_add_f32_e32 v112, v160, v112
	v_add_f32_e32 v112, v127, v112
	v_add_f32_e32 v112, v161, v112
	v_add_f32_e32 v112, v158, v112
	v_add_f32_e32 v112, v162, v112
	v_add_f32_e32 v112, v159, v112
	v_add_f32_e32 v112, v163, v112
	v_add_f32_e32 v112, v118, v112
	v_add_f32_e32 v112, v121, v112
	v_add_f32_e32 v112, v119, v112
	v_add_f32_e32 v112, v122, v112
	v_add_f32_e32 v112, v120, v112
	v_add_f32_e32 v112, v123, v112
	v_add_f32_e32 v112, v124, v112
	v_exp_f32_e32 v165, v113
	v_add_f32_e32 v112, v125, v112
	v_add_f32_e32 v112, v117, v112
	v_add_f32_e32 v112, v157, v112
	v_add_f32_e32 v112, v164, v112
	v_add_f32_e32 v112, v165, v112
	v_add_f32_e32 v112, v108, v112
	v_add_f32_e32 v112, v109, v112
	v_add_f32_e32 v112, v104, v112
	v_add_f32_e32 v112, v105, v112
	v_add_f32_e32 v112, v102, v112
	v_add_f32_e32 v112, v103, v112
	v_add_f32_e32 v112, v110, v112
	v_add_f32_e32 v112, v111, v112
	v_add_f32_e32 v112, v106, v112
	v_add_f32_e32 v112, v107, v112
	v_add_f32_e32 v112, v100, v112
	v_add_f32_e32 v155, v101, v112
	v_mov_b32_e32 v156, v155
	v_cvt_pk_bf16_f32 v214, v126, v160
	v_cvt_pk_bf16_f32 v215, v127, v161
	v_cvt_pk_bf16_f32 v216, v158, v162
	s_nop 1
	v_permlane32_swap_b32_e32 v155, v156
	v_cvt_pk_bf16_f32 v217, v159, v163
	v_permlane32_swap_b32_e32 v214, v216
	v_cvt_pk_bf16_f32 v218, v118, v121
	v_cvt_pk_bf16_f32 v219, v119, v122
	v_cvt_pk_bf16_f32 v220, v120, v123
	v_cvt_pk_bf16_f32 v221, v124, v125
	v_cvt_pk_bf16_f32 v222, v117, v157
	v_cvt_pk_bf16_f32 v223, v164, v165
	v_cvt_pk_bf16_f32 v224, v108, v109
	v_cvt_pk_bf16_f32 v225, v104, v105
	v_cvt_pk_bf16_f32 v226, v102, v103
	v_cvt_pk_bf16_f32 v227, v110, v111
	v_cvt_pk_bf16_f32 v228, v106, v107
	v_cvt_pk_bf16_f32 v229, v100, v101
	v_permlane32_swap_b32_e32 v215, v217
	v_permlane32_swap_b32_e32 v218, v220
	v_permlane32_swap_b32_e32 v219, v221
	v_permlane32_swap_b32_e32 v222, v224
	v_permlane32_swap_b32_e32 v223, v225
	v_permlane32_swap_b32_e32 v226, v228
	v_permlane32_swap_b32_e32 v227, v229
	s_cmpk_lt_u32 s25, 0x7e
	s_cselect_b32 s0, 0, 0xffffff80
	s_cselect_b32 s1, s10, s24
	s_add_i32 s0, s0, s11
	s_lshl_b32 s0, s0, 6
	s_add_i32 s0, s0, s1
	s_sub_i32 s0, s0, 64
	s_ashr_i32 s1, s0, 31
	s_cmpk_lt_u32 s25, 0x7f
	s_cselect_b32 s98, 0, 0xffffff80
	s_cselect_b32 s99, s10, s24
	s_add_i32 s98, s98, s11
	s_lshl_b32 s98, s98, 6
	s_add_i32 s98, s98, s99
	s_addk_i32 s98, 0xff80
	s_ashr_i32 s99, s98, 31
	v_lshl_add_u64 v[100:101], s[0:1], 0, v[130:131]
	v_lshl_add_u64 v[104:105], s[98:99], 0, v[130:131]
	v_lshlrev_b64 v[104:105], 9, v[104:105]
	v_lshl_add_u64 v[104:105], v[134:135], 0, v[104:105]
	v_mad_u64_u32 v[102:103], s[12:13], v100, s70, v[136:137]
	v_or_b32_e32 v106, s0, v132
	v_mad_i32_i24 v103, v101, s70, v103
	v_mad_i64_i32 v[106:107], s[0:1], v106, s70, v[138:139]
	global_load_dwordx4 v[184:187], v[102:103], off
	s_nop 0
	global_load_dwordx4 v[188:191], v[104:105], off
	s_nop 0
	global_load_dwordx4 v[230:233], v[106:107], off offset:128
	ds_read_b64_tr_b16 v[192:193], v144 offset:0
	ds_read_b64_tr_b16 v[194:195], v144 offset:0x800
	ds_read_b64_tr_b16 v[196:197], v144 offset:0x1000
	ds_read_b64_tr_b16 v[198:199], v144 offset:0x1800
	ds_read_b64_tr_b16 v[200:201], v144 offset:0x2000
	ds_read_b64_tr_b16 v[202:203], v144 offset:0x2800
	ds_read_b64_tr_b16 v[210:211], v144 offset:0x3000
	ds_read_b64_tr_b16 v[212:213], v144 offset:0x3800
	s_waitcnt lgkmcnt(0)
	s_nop 0
	v_mfma_f32_32x32x16_bf16 v[0:15], v[214:217], v[192:195], v[0:15]
	ds_read_b64_tr_b16 v[192:193], v144 offset:0x200
	ds_read_b64_tr_b16 v[194:195], v144 offset:0xa00
	v_mfma_f32_32x32x16_bf16 v[0:15], v[218:221], v[196:199], v[0:15]
	ds_read_b64_tr_b16 v[196:197], v144 offset:0x1200
	ds_read_b64_tr_b16 v[198:199], v144 offset:0x1a00
	v_mfma_f32_32x32x16_bf16 v[0:15], v[222:225], v[200:203], v[0:15]
	ds_read_b64_tr_b16 v[200:201], v144 offset:0x2200
	ds_read_b64_tr_b16 v[202:203], v144 offset:0x2a00
	v_mfma_f32_32x32x16_bf16 v[0:15], v[226:229], v[210:213], v[0:15]
	ds_read_b64_tr_b16 v[210:211], v144 offset:0x3200
	ds_read_b64_tr_b16 v[212:213], v144 offset:0x3a00
	s_waitcnt lgkmcnt(0)
	v_mfma_f32_32x32x16_bf16 v[16:31], v[214:217], v[192:195], v[16:31]
	v_mfma_f32_32x32x16_bf16 v[16:31], v[218:221], v[196:199], v[16:31]
	v_mfma_f32_32x32x16_bf16 v[16:31], v[222:225], v[200:203], v[16:31]
	v_mfma_f32_32x32x16_bf16 v[16:31], v[226:229], v[210:213], v[16:31]
	ds_read_b128 v[32:35], v148 offset:49152
	ds_read_b128 v[36:39], v148 offset:57344
	ds_read_b128 v[164:167], v152 offset:49152
	ds_read_b128 v[168:171], v152 offset:57344
	s_waitcnt lgkmcnt(3)
	v_mfma_f32_32x32x16_bf16 v[48:63], v[32:35], v[84:87], 0
	s_waitcnt lgkmcnt(2)
	v_mfma_f32_32x32x16_bf16 v[32:47], v[36:39], v[84:87], 0
	s_waitcnt lgkmcnt(1)
	v_mfma_f32_32x32x16_bf16 v[48:63], v[164:167], v[80:83], v[48:63]
	s_waitcnt lgkmcnt(0)
	v_mfma_f32_32x32x16_bf16 v[32:47], v[168:171], v[80:83], v[32:47]
	ds_read_b128 v[164:167], v151 offset:49152
	ds_read_b128 v[168:171], v151 offset:57344
	s_waitcnt lgkmcnt(1)
	v_mfma_f32_32x32x16_bf16 v[48:63], v[164:167], v[76:79], v[48:63]
	s_waitcnt lgkmcnt(0)
; template <int DQK> __device__ __forceinline__ void partialSM(f32x16& p0, f32x16& p1, float& m_reg, float& mn, float& alpha) {
;   constexpr float SCALE = (DQK == 96) ? 0.10206207261596577f : 0.125f;
;   constexpr float C = SCALE * 1.4426950408889634f;
;   float pmax = p0[0];
; #pragma unroll
;   for (int r = 1; r < 16; ++r) pmax = fmaxf(pmax, p0[r]);
; #pragma unroll
;   for (int r = 0; r < 16; ++r) pmax = fmaxf(pmax, p1[r]);
;   { auto rr = __builtin_amdgcn_permlane32_swap(__float_as_uint(pmax), __float_as_uint(pmax), false, false);
;     pmax = fmaxf(__uint_as_float(rr[0]), __uint_as_float(rr[1])); }
;   if (__builtin_expect(__all(pmax - m_reg <= THR / SCALE), 1)) { mn = m_reg; alpha = 1.f; }
;   else { mn = fmaxf(m_reg, pmax); alpha = __builtin_amdgcn_exp2f((m_reg - mn) * C); m_reg = mn; }
;   float mnC = -mn * C;
; #pragma unroll
;   for (int r = 0; r < 16; ++r) p0[r] = fmaf(p0[r], C, mnC);
; #pragma unroll
;   for (int r = 0; r < 16; ++r) p1[r] = fmaf(p1[r], C, mnC);
; #pragma unroll
;   for (int r = 0; r < 16; ++r) p0[r] = __builtin_amdgcn_exp2f(p0[r]);
; }
	v_mfma_f32_32x32x16_bf16 v[32:47], v[168:171], v[76:79], v[32:47]
	ds_read_b128 v[164:167], v149 offset:49152
	ds_read_b128 v[168:171], v149 offset:57344
	s_waitcnt lgkmcnt(1)
	v_mfma_f32_32x32x16_bf16 v[48:63], v[164:167], v[72:75], v[48:63]
	s_waitcnt lgkmcnt(0)
	v_mfma_f32_32x32x16_bf16 v[32:47], v[168:171], v[72:75], v[32:47]
	ds_read_b128 v[164:167], v150 offset:49152
	ds_read_b128 v[168:171], v150 offset:57344
	s_waitcnt lgkmcnt(1)
	v_mfma_f32_32x32x16_bf16 v[48:63], v[164:167], v[68:71], v[48:63]
	s_waitcnt lgkmcnt(0)
	v_mfma_f32_32x32x16_bf16 v[32:47], v[168:171], v[68:71], v[32:47]
	ds_read_b128 v[164:167], v153 offset:49152
	ds_read_b128 v[168:171], v153 offset:57344
	s_waitcnt lgkmcnt(1)
	v_mfma_f32_32x32x16_bf16 v[48:63], v[164:167], v[64:67], v[48:63]
	s_waitcnt lgkmcnt(0)
	v_mfma_f32_32x32x16_bf16 v[32:47], v[168:171], v[64:67], v[32:47]
	s_nop 7
	s_nop 4
	v_max_f32_e32 v112, v49, v49
	v_max_f32_e32 v113, v48, v48
	v_max_f32_e32 v112, v113, v112
	v_max3_f32 v112, v112, v50, v51
	v_max3_f32 v112, v112, v52, v53
	v_max3_f32 v112, v112, v54, v55
	v_max3_f32 v112, v112, v56, v57
	v_max3_f32 v112, v112, v58, v59
	v_max3_f32 v112, v112, v60, v61
	v_max3_f32 v112, v112, v62, v63
	v_max3_f32 v112, v112, v32, v33
	v_max3_f32 v112, v112, v34, v35
	v_max3_f32 v112, v112, v36, v37
	v_max3_f32 v112, v112, v38, v39
	v_max3_f32 v112, v112, v40, v41
	v_max3_f32 v112, v112, v42, v43
	v_max3_f32 v112, v112, v44, v45
	v_max3_f32 v112, v112, v46, v47
	v_mov_b32_e32 v113, v112
	s_nop 1
	v_permlane32_swap_b32_e32 v112, v113
	v_max_f32_e32 v113, v113, v113
	v_max_f32_e32 v112, v112, v112
	v_max_f32_e32 v112, v112, v113
	v_sub_f32_e32 v113, v112, v116
	v_cmp_ge_f32_e32 vcc, s80, v113
	v_max_f32_e32 v113, v116, v116
	v_max_f32_e32 v112, v113, v112
	v_sub_f32_e32 v113, v116, v112
	v_mul_f32_e32 v113, 0x3e16c740, v113
	v_exp_f32_e32 v113, v113
	s_cmp_eq_u64 vcc, exec
	s_cselect_b64 s[0:1], -1, 0
	v_cndmask_b32_e64 v157, v113, 1.0, s[0:1]
	v_cmp_gt_f32_e32 vcc, 1.0, v157
	v_cndmask_b32_e64 v158, v112, v116, s[0:1]
	v_mul_f32_e32 v159, 0xbe16c740, v158
	v_fmamk_f32 v48, v48, 0x3e16c740, v159
	v_fmamk_f32 v49, v49, 0x3e16c740, v159
	v_fmamk_f32 v50, v50, 0x3e16c740, v159
	v_fmamk_f32 v51, v51, 0x3e16c740, v159
	v_fmamk_f32 v52, v52, 0x3e16c740, v159
	v_fmamk_f32 v53, v53, 0x3e16c740, v159
	v_fmamk_f32 v54, v54, 0x3e16c740, v159
	v_fmamk_f32 v55, v55, 0x3e16c740, v159
	v_fmamk_f32 v56, v56, 0x3e16c740, v159
	v_fmamk_f32 v57, v57, 0x3e16c740, v159
	v_fmamk_f32 v58, v58, 0x3e16c740, v159
	v_fmamk_f32 v59, v59, 0x3e16c740, v159
	v_fmamk_f32 v60, v60, 0x3e16c740, v159
	v_fmamk_f32 v61, v61, 0x3e16c740, v159
	v_fmamk_f32 v62, v62, 0x3e16c740, v159
	v_fmamk_f32 v63, v63, 0x3e16c740, v159
	v_exp_f32_e32 v112, v48
	v_exp_f32_e32 v127, v49
	v_exp_f32_e32 v113, v50
	v_exp_f32_e32 v126, v51
	v_exp_f32_e32 v114, v52
	v_exp_f32_e32 v125, v53
	v_exp_f32_e32 v115, v54
	v_exp_f32_e32 v124, v55
	v_exp_f32_e32 v116, v56
	v_exp_f32_e32 v123, v57
	v_exp_f32_e32 v117, v58
	v_exp_f32_e32 v122, v59
	v_exp_f32_e32 v118, v60
	v_exp_f32_e32 v121, v61
	v_exp_f32_e32 v119, v62
	v_exp_f32_e32 v120, v63
	v_fmamk_f32 v164, v42, 0x3e16c740, v159
	v_fmamk_f32 v165, v43, 0x3e16c740, v159
	v_fmamk_f32 v167, v32, 0x3e16c740, v159
	v_fmamk_f32 v168, v33, 0x3e16c740, v159
	v_fmamk_f32 v169, v34, 0x3e16c740, v159
	v_fmamk_f32 v170, v35, 0x3e16c740, v159
	v_fmamk_f32 v171, v36, 0x3e16c740, v159
	v_fmamk_f32 v172, v37, 0x3e16c740, v159
	v_fmamk_f32 v160, v38, 0x3e16c740, v159
	v_fmamk_f32 v161, v39, 0x3e16c740, v159
	v_fmamk_f32 v162, v40, 0x3e16c740, v159
	v_fmamk_f32 v163, v41, 0x3e16c740, v159
	v_fmamk_f32 v166, v44, 0x3e16c740, v159
	v_fmamk_f32 v173, v45, 0x3e16c740, v159
	v_fmamk_f32 v174, v46, 0x3e16c740, v159
	v_fmac_f32_e32 v159, 0x3e16c740, v47
	s_cbranch_vccz .Lmy_h1B_304
	s_and_saveexec_b64 s[12:13], s[4:5]
	ds_write_b32 v141, v157 offset:128
	s_or_b64 exec, exec, s[12:13]
	s_waitcnt lgkmcnt(0)
	ds_read_b128 v[192:195], v129 offset:224
	ds_read_b128 v[196:199], v129 offset:192
	ds_read_b128 v[200:203], v129 offset:160
	ds_read_b128 v[210:213], v129 offset:128
	s_waitcnt lgkmcnt(3)
	v_pk_mul_f32 v[14:15], v[14:15], v[194:195]
	s_waitcnt lgkmcnt(2)
	v_pk_mul_f32 v[10:11], v[10:11], v[198:199]
	s_waitcnt lgkmcnt(1)
	v_pk_mul_f32 v[6:7], v[6:7], v[202:203]
	s_waitcnt lgkmcnt(0)
	v_pk_mul_f32 v[2:3], v[2:3], v[212:213]
	v_pk_mul_f32 v[12:13], v[12:13], v[192:193]
	v_pk_mul_f32 v[8:9], v[8:9], v[196:197]
	v_pk_mul_f32 v[4:5], v[4:5], v[200:201]
	v_pk_mul_f32 v[0:1], v[0:1], v[210:211]
	v_pk_mul_f32 v[30:31], v[30:31], v[194:195]
	v_pk_mul_f32 v[26:27], v[26:27], v[198:199]
	v_pk_mul_f32 v[22:23], v[22:23], v[202:203]
	v_pk_mul_f32 v[18:19], v[18:19], v[212:213]
	v_pk_mul_f32 v[28:29], v[28:29], v[192:193]
	v_pk_mul_f32 v[24:25], v[24:25], v[196:197]
	v_pk_mul_f32 v[20:21], v[20:21], v[200:201]
	v_pk_mul_f32 v[16:17], v[16:17], v[210:211]
; #define SBAR() __builtin_amdgcn_sched_barrier(0)
; __device__ __forceinline__ void finishSM(f32x16& p0, f32x16& p1, float alpha, float& l_reg, bf16x8& pa0, bf16x8& pa1, bf16x8& pa2, bf16x8& pa3) {
; #pragma unroll
;   for (int r = 0; r < 16; ++r) p1[r] = __builtin_amdgcn_exp2f(p1[r]);
;   float ps = 0;
; #pragma unroll
;   for (int r = 0; r < 16; ++r) ps += p0[r];
; #pragma unroll
;   for (int r = 0; r < 16; ++r) ps += p1[r];
;   { auto rr = __builtin_amdgcn_permlane32_swap(__float_as_uint(ps), __float_as_uint(ps), false, false);
;     ps = __uint_as_float(rr[0]) + __uint_as_float(rr[1]); }
;   l_reg = l_reg * alpha + ps;
;     ...
;   PK4(p0, 0, pa0); PK4(p0, 8, pa1); PK4(p1, 0, pa2); PK4(p1, 8, pa3);
;     ...
; }
; template <int DQK> __device__ __forceinline__ void qkt(f32x16& p0, f32x16& p1, const char* Ks, const bf16x8* qr, int r32, int hi) {
;   p0 = f32x16{}; p1 = f32x16{};
; #pragma unroll
;   for (int d0 = 0; d0 < DQK / 16; ++d0) { int cb = (d0 * 16 + hi * 8) * 2;
;     bf16x8 b0 = *reinterpret_cast<const bf16x8*>(Ks + KSWZ(r32, cb));
;     bf16x8 b1 = *reinterpret_cast<const bf16x8*>(Ks + KSWZ(32 + r32, cb));
;     p0 = __builtin_amdgcn_mfma_f32_32x32x16_bf16(b0, qr[d0], p0, 0, 0, 0);
;     p1 = __builtin_amdgcn_mfma_f32_32x32x16_bf16(b1, qr[d0], p1, 0, 0, 0); }
; }
; __device__ __forceinline__ int v_st(int k, int c) { const int kk = (k & ~0xC) | ((k & 4) << 1) | ((k & 8) >> 1); return ((kk >> 3) * 4 + (c >> 5)) * 512 + ((kk & 7) * 32 + (c & 31)) * 2; }
; __device__ __forceinline__ int v_rd_base(int lane) { return ((lane & 3) << 3) | (((lane >> 2) & 3) << 6) | (((lane >> 4) & 1) << 5) | (((lane >> 5) & 1) << 8); }
; template <int OFF> __device__ __forceinline__ s16x4 tr_read(int vb) {
;   s16x4 r; asm volatile("ds_read_b64_tr_b16 %0, %1 offset:%2" : "=&v"(r) : "v"(vb), "i"(OFF) : "memory"); return r;
; }
; template <int D0> __device__ __forceinline__ void pv_one(f32x16& od, int vb, bf16x8 pa0, bf16x8 pa1, bf16x8 pa2, bf16x8 pa3) {
; template <int DQK, int MODE, int ldq, int ldk, int ldv> ...
;     ...
;     __syncthreads(); SWRITE(0, SE);
;     RESC(alB); __syncthreads();
;     SBAR(); qkt<DQK>(pA0, pA1, K_lds, qr, r32, hi);
;     finishSM(pB0, pB1, alB, l_reg, pa0, pa1, pa2, pa3); SBAR();
;     if (j + 3 < NT) SLOAD(SE, j + 3); SBAR();
;     pv_d0(o, vb0 + (int)SHM_V, pa0, pa1, pa2, pa3); BIAS(pA0, pA1, j + 1); partialSM<DQK>(pA0, pA1, m_reg, mnA, alA);
.Lmy_h1B_304:
	s_waitcnt lgkmcnt(0)
	s_barrier
	s_waitcnt vmcnt(0)
	ds_write_b128 v146, v[184:187] offset:49152
	ds_write_b128 v147, v[230:233] offset:49152
	ds_write_b128 v145, v[188:191]
	v_exp_f32_e32 v175, v164
	v_add_f32_e32 v164, 0, v112
	v_add_f32_e32 v164, v127, v164
	v_add_f32_e32 v164, v113, v164
	v_add_f32_e32 v164, v126, v164
	v_add_f32_e32 v164, v114, v164
	v_add_f32_e32 v164, v125, v164
	v_add_f32_e32 v164, v115, v164
	v_add_f32_e32 v164, v124, v164
	v_add_f32_e32 v164, v116, v164
	v_add_f32_e32 v164, v123, v164
	v_add_f32_e32 v164, v117, v164
	v_add_f32_e32 v164, v122, v164
	v_exp_f32_e32 v167, v167
	v_add_f32_e32 v164, v118, v164
	v_exp_f32_e32 v168, v168
	v_add_f32_e32 v164, v121, v164
	v_exp_f32_e32 v169, v169
	v_add_f32_e32 v164, v119, v164
	v_exp_f32_e32 v170, v170
	v_add_f32_e32 v164, v120, v164
	v_exp_f32_e32 v171, v171
	v_add_f32_e32 v164, v167, v164
	v_exp_f32_e32 v172, v172
	v_add_f32_e32 v164, v168, v164
	v_exp_f32_e32 v160, v160
	v_add_f32_e32 v164, v169, v164
	v_exp_f32_e32 v161, v161
	v_add_f32_e32 v164, v170, v164
	v_exp_f32_e32 v162, v162
	v_add_f32_e32 v164, v171, v164
	v_exp_f32_e32 v163, v163
	v_add_f32_e32 v164, v172, v164
	v_add_f32_e32 v164, v160, v164
	v_add_f32_e32 v164, v161, v164
	v_exp_f32_e32 v166, v166
	v_add_f32_e32 v164, v162, v164
	v_exp_f32_e32 v173, v173
	v_add_f32_e32 v164, v163, v164
	v_exp_f32_e32 v174, v174
	v_add_f32_e32 v164, v175, v164
	v_exp_f32_e32 v159, v159
	v_cvt_pk_bf16_f32 v214, v112, v127
	v_cvt_pk_bf16_f32 v215, v113, v126
	v_cvt_pk_bf16_f32 v216, v114, v125
	v_cvt_pk_bf16_f32 v217, v115, v124
	v_cvt_pk_bf16_f32 v218, v116, v123
	v_cvt_pk_bf16_f32 v219, v117, v122
	v_exp_f32_e32 v176, v165
	v_cvt_pk_bf16_f32 v220, v118, v121
	v_cvt_pk_bf16_f32 v221, v119, v120
	v_cvt_pk_bf16_f32 v222, v167, v168
	v_cvt_pk_bf16_f32 v223, v169, v170
	v_cvt_pk_bf16_f32 v224, v171, v172
	s_nop 0
	v_add_f32_e32 v164, v176, v164
	v_add_f32_e32 v164, v166, v164
	v_add_f32_e32 v164, v173, v164
	v_add_f32_e32 v164, v174, v164
	v_add_f32_e32 v164, v159, v164
	v_mov_b32_e32 v165, v164
	v_cvt_pk_bf16_f32 v225, v160, v161
	v_cvt_pk_bf16_f32 v226, v162, v163
	v_cvt_pk_bf16_f32 v227, v175, v176
	v_cvt_pk_bf16_f32 v228, v166, v173
	v_cvt_pk_bf16_f32 v229, v174, v159
	s_nop 1
	v_permlane32_swap_b32_e32 v164, v165
	v_permlane32_swap_b32_e32 v214, v216
	v_permlane32_swap_b32_e32 v215, v217
	v_permlane32_swap_b32_e32 v218, v220
	v_permlane32_swap_b32_e32 v219, v221
	v_permlane32_swap_b32_e32 v222, v224
	v_permlane32_swap_b32_e32 v223, v225
	v_permlane32_swap_b32_e32 v226, v228
	v_permlane32_swap_b32_e32 v227, v229
	s_cmpk_lt_u32 s25, 0x7e
	s_cselect_b32 s98, 0, 0xffffff80
	s_cselect_b32 s99, s10, s24
	s_add_i32 s98, s98, s11
	s_lshl_b32 s98, s98, 6
	s_add_i32 s98, s98, s99
	s_sub_i32 s98, s98, 64
	s_ashr_i32 s99, s98, 31
	v_lshl_add_u64 v[92:93], s[98:99], 0, v[130:131]
	v_lshlrev_b64 v[92:93], 9, v[92:93]
	v_lshl_add_u64 v[92:93], v[134:135], 0, v[92:93]
	global_load_dwordx4 v[92:95], v[92:93], off
	s_cmpk_gt_u32 s25, 0x80
	s_cbranch_scc1 .Lmy_h2B_306
	s_cmpk_lt_u32 s25, 0x7d
	s_cselect_b32 s0, 0, 0xffffff80
	s_cselect_b32 s1, s10, s24
	s_add_i32 s0, s0, s11
	s_lshl_b32 s0, s0, 6
	s_add_i32 s0, s0, s1
	s_ashr_i32 s1, s0, 31
	v_lshl_add_u64 v[88:89], s[0:1], 0, v[130:131]
	v_mad_u64_u32 v[90:91], s[12:13], v88, s70, v[136:137]
	v_or_b32_e32 v96, s0, v132
	v_mad_i32_i24 v91, v89, s70, v91
	v_mad_i64_i32 v[96:97], s[0:1], v96, s70, v[138:139]
	global_load_dwordx4 v[88:91], v[90:91], off
	s_nop 0
	s_nop 0
	global_load_dwordx4 v[96:99], v[96:97], off offset:128
.Lmy_h2B_306:
	ds_read_b64_tr_b16 v[192:193], v143 offset:0
	ds_read_b64_tr_b16 v[194:195], v143 offset:0x800
	ds_read_b64_tr_b16 v[196:197], v143 offset:0x1000
	ds_read_b64_tr_b16 v[198:199], v143 offset:0x1800
	ds_read_b64_tr_b16 v[200:201], v143 offset:0x2000
	ds_read_b64_tr_b16 v[202:203], v143 offset:0x2800
	ds_read_b64_tr_b16 v[210:211], v143 offset:0x3000
	ds_read_b64_tr_b16 v[212:213], v143 offset:0x3800
	s_waitcnt lgkmcnt(0)
	s_nop 0
	v_mfma_f32_32x32x16_bf16 v[0:15], v[214:217], v[192:195], v[0:15]
	ds_read_b64_tr_b16 v[192:193], v143 offset:0x200
	ds_read_b64_tr_b16 v[194:195], v143 offset:0xa00
	v_mfma_f32_32x32x16_bf16 v[0:15], v[218:221], v[196:199], v[0:15]
	ds_read_b64_tr_b16 v[196:197], v143 offset:0x1200
	ds_read_b64_tr_b16 v[198:199], v143 offset:0x1a00
	v_mfma_f32_32x32x16_bf16 v[0:15], v[222:225], v[200:203], v[0:15]
	ds_read_b64_tr_b16 v[200:201], v143 offset:0x2200
	ds_read_b64_tr_b16 v[202:203], v143 offset:0x2a00
	v_mfma_f32_32x32x16_bf16 v[0:15], v[226:229], v[210:213], v[0:15]
	ds_read_b64_tr_b16 v[210:211], v143 offset:0x3200
	ds_read_b64_tr_b16 v[212:213], v143 offset:0x3a00
	s_waitcnt lgkmcnt(0)
	v_mfma_f32_32x32x16_bf16 v[16:31], v[214:217], v[192:195], v[16:31]
	v_mfma_f32_32x32x16_bf16 v[16:31], v[218:221], v[196:199], v[16:31]
	v_mfma_f32_32x32x16_bf16 v[16:31], v[222:225], v[200:203], v[16:31]
	v_mfma_f32_32x32x16_bf16 v[16:31], v[226:229], v[210:213], v[16:31]
	ds_read_b128 v[32:35], v148 offset:32768
	ds_read_b128 v[36:39], v148 offset:40960
	ds_read_b128 v[176:179], v152 offset:32768
	ds_read_b128 v[180:183], v152 offset:40960
	s_waitcnt lgkmcnt(3)
	v_mfma_f32_32x32x16_bf16 v[48:63], v[32:35], v[84:87], 0
	s_waitcnt lgkmcnt(2)
	v_mfma_f32_32x32x16_bf16 v[32:47], v[36:39], v[84:87], 0
	s_waitcnt lgkmcnt(1)
; template <int DQK> __device__ __forceinline__ void partialSM(f32x16& p0, f32x16& p1, float& m_reg, float& mn, float& alpha) {
;   constexpr float SCALE = (DQK == 96) ? 0.10206207261596577f : 0.125f;
;   constexpr float C = SCALE * 1.4426950408889634f;
;   float pmax = p0[0];
; #pragma unroll
;   for (int r = 1; r < 16; ++r) pmax = fmaxf(pmax, p0[r]);
; #pragma unroll
;   for (int r = 0; r < 16; ++r) pmax = fmaxf(pmax, p1[r]);
;   { auto rr = __builtin_amdgcn_permlane32_swap(__float_as_uint(pmax), __float_as_uint(pmax), false, false);
;     pmax = fmaxf(__uint_as_float(rr[0]), __uint_as_float(rr[1])); }
;   if (__builtin_expect(__all(pmax - m_reg <= THR / SCALE), 1)) { mn = m_reg; alpha = 1.f; }
;   else { mn = fmaxf(m_reg, pmax); alpha = __builtin_amdgcn_exp2f((m_reg - mn) * C); m_reg = mn; }
;   float mnC = -mn * C;
; #pragma unroll
;   for (int r = 0; r < 16; ++r) p0[r] = fmaf(p0[r], C, mnC);
; #pragma unroll
;   for (int r = 0; r < 16; ++r) p1[r] = fmaf(p1[r], C, mnC);
; #pragma unroll
;   for (int r = 0; r < 16; ++r) p0[r] = __builtin_amdgcn_exp2f(p0[r]);
; }
	v_mfma_f32_32x32x16_bf16 v[48:63], v[176:179], v[80:83], v[48:63]
	s_waitcnt lgkmcnt(0)
	v_mfma_f32_32x32x16_bf16 v[32:47], v[180:183], v[80:83], v[32:47]
	ds_read_b128 v[176:179], v151 offset:32768
	ds_read_b128 v[180:183], v151 offset:40960
	s_waitcnt lgkmcnt(1)
	v_mfma_f32_32x32x16_bf16 v[48:63], v[176:179], v[76:79], v[48:63]
	s_waitcnt lgkmcnt(0)
	v_mfma_f32_32x32x16_bf16 v[32:47], v[180:183], v[76:79], v[32:47]
	ds_read_b128 v[176:179], v149 offset:32768
	ds_read_b128 v[180:183], v149 offset:40960
	s_waitcnt lgkmcnt(1)
	v_mfma_f32_32x32x16_bf16 v[48:63], v[176:179], v[72:75], v[48:63]
	s_waitcnt lgkmcnt(0)
	v_mfma_f32_32x32x16_bf16 v[32:47], v[180:183], v[72:75], v[32:47]
	ds_read_b128 v[176:179], v150 offset:32768
	ds_read_b128 v[180:183], v150 offset:40960
	s_waitcnt lgkmcnt(1)
	v_mfma_f32_32x32x16_bf16 v[48:63], v[176:179], v[68:71], v[48:63]
	s_waitcnt lgkmcnt(0)
	v_mfma_f32_32x32x16_bf16 v[32:47], v[180:183], v[68:71], v[32:47]
	ds_read_b128 v[176:179], v153 offset:32768
	ds_read_b128 v[180:183], v153 offset:40960
	s_waitcnt lgkmcnt(1)
	v_mfma_f32_32x32x16_bf16 v[48:63], v[176:179], v[64:67], v[48:63]
	s_waitcnt lgkmcnt(0)
	v_mfma_f32_32x32x16_bf16 v[32:47], v[180:183], v[64:67], v[32:47]
	s_nop 7
	s_nop 4
	v_max_f32_e32 v112, v49, v49
	v_max_f32_e32 v113, v48, v48
	v_max_f32_e32 v112, v113, v112
	v_max3_f32 v112, v112, v50, v51
	v_max3_f32 v112, v112, v52, v53
	v_max3_f32 v112, v112, v54, v55
	v_max3_f32 v112, v112, v56, v57
	v_max3_f32 v112, v112, v58, v59
	v_max3_f32 v112, v112, v60, v61
	v_max3_f32 v112, v112, v62, v63
	v_max3_f32 v112, v112, v32, v33
	v_max3_f32 v112, v112, v34, v35
	v_max3_f32 v112, v112, v36, v37
	v_max3_f32 v112, v112, v38, v39
	v_max3_f32 v112, v112, v40, v41
	v_max3_f32 v112, v112, v42, v43
	v_max3_f32 v112, v112, v44, v45
	v_max3_f32 v112, v112, v46, v47
	v_mov_b32_e32 v113, v112
	s_nop 1
	v_permlane32_swap_b32_e32 v112, v113
	v_max_f32_e32 v113, v113, v113
	v_max_f32_e32 v112, v112, v112
	v_max_f32_e32 v112, v112, v113
	v_sub_f32_e32 v113, v112, v158
	v_cmp_ge_f32_e32 vcc, s80, v113
	v_max_f32_e32 v113, v158, v158
	v_max_f32_e32 v112, v113, v112
	v_sub_f32_e32 v113, v158, v112
	v_mul_f32_e32 v113, 0x3e16c740, v113
	v_exp_f32_e32 v113, v113
	s_cmp_eq_u64 vcc, exec
	s_cselect_b64 s[0:1], -1, 0
	v_cndmask_b32_e64 v117, v113, 1.0, s[0:1]
	v_cmp_gt_f32_e32 vcc, 1.0, v117
	v_cndmask_b32_e64 v116, v112, v158, s[0:1]
	v_mul_f32_e32 v100, 0xbe16c740, v116
	v_mov_b32_e32 v101, v100
	v_fmamk_f32 v48, v48, 0x3e16c740, v100
	v_fmamk_f32 v49, v49, 0x3e16c740, v100
	v_fmamk_f32 v50, v50, 0x3e16c740, v100
	v_fmamk_f32 v51, v51, 0x3e16c740, v100
	v_fmamk_f32 v52, v52, 0x3e16c740, v100
	v_fmamk_f32 v53, v53, 0x3e16c740, v100
	v_fmamk_f32 v54, v54, 0x3e16c740, v100
	v_fmamk_f32 v55, v55, 0x3e16c740, v100
	v_fmamk_f32 v56, v56, 0x3e16c740, v100
	v_fmamk_f32 v57, v57, 0x3e16c740, v100
	v_fmamk_f32 v58, v58, 0x3e16c740, v100
	v_fmamk_f32 v59, v59, 0x3e16c740, v100
	v_fmamk_f32 v60, v60, 0x3e16c740, v100
	v_fmamk_f32 v61, v61, 0x3e16c740, v100
	v_fmamk_f32 v62, v62, 0x3e16c740, v100
	v_fmac_f32_e32 v101, 0x3e16c740, v63
	v_exp_f32_e32 v126, v48
	v_exp_f32_e32 v160, v49
	v_exp_f32_e32 v127, v50
	v_exp_f32_e32 v161, v51
	v_exp_f32_e32 v158, v52
	v_exp_f32_e32 v162, v53
	v_exp_f32_e32 v159, v54
	v_exp_f32_e32 v163, v55
	v_exp_f32_e32 v118, v56
	v_exp_f32_e32 v121, v57
	v_exp_f32_e32 v119, v58
	v_exp_f32_e32 v122, v59
	v_exp_f32_e32 v120, v60
	v_exp_f32_e32 v123, v61
	v_exp_f32_e32 v124, v62
	v_exp_f32_e32 v125, v101
	v_pk_fma_f32 v[114:115], v[32:33], s[40:41], v[100:101] op_sel_hi:[1,0,0]
	v_add_f32_e32 v32, v155, v156
	v_fmac_f32_e32 v32, v154, v142
	v_add_f32_e32 v142, v164, v165
	v_pk_fma_f32 v[112:113], v[34:35], s[40:41], v[100:101] op_sel_hi:[1,0,0]
	v_pk_fma_f32 v[108:109], v[36:37], s[40:41], v[100:101] op_sel_hi:[1,0,0]
	v_pk_fma_f32 v[104:105], v[38:39], s[40:41], v[100:101] op_sel_hi:[1,0,0]
	v_pk_fma_f32 v[102:103], v[40:41], s[40:41], v[100:101] op_sel_hi:[1,0,0]
	v_pk_fma_f32 v[110:111], v[42:43], s[40:41], v[100:101] op_sel_hi:[1,0,0]
	v_pk_fma_f32 v[106:107], v[44:45], s[40:41], v[100:101] op_sel_hi:[1,0,0]
	v_pk_fma_f32 v[100:101], v[46:47], s[40:41], v[100:101] op_sel_hi:[1,0,0]
	v_fmac_f32_e32 v142, v32, v157
	s_cbranch_vccz .Lmy_h2B_310
	s_and_saveexec_b64 s[12:13], s[4:5]
	ds_write_b32 v141, v117 offset:128
	s_or_b64 exec, exec, s[12:13]
	s_waitcnt lgkmcnt(0)
	ds_read_b128 v[192:195], v129 offset:224
	ds_read_b128 v[196:199], v129 offset:192
	ds_read_b128 v[200:203], v129 offset:160
	ds_read_b128 v[210:213], v129 offset:128
	s_waitcnt lgkmcnt(3)
	v_pk_mul_f32 v[14:15], v[14:15], v[194:195]
	s_waitcnt lgkmcnt(2)
	v_pk_mul_f32 v[10:11], v[10:11], v[198:199]
	s_waitcnt lgkmcnt(1)
	v_pk_mul_f32 v[6:7], v[6:7], v[202:203]
	s_waitcnt lgkmcnt(0)
	v_pk_mul_f32 v[2:3], v[2:3], v[212:213]
	v_pk_mul_f32 v[12:13], v[12:13], v[192:193]
	v_pk_mul_f32 v[8:9], v[8:9], v[196:197]
	v_pk_mul_f32 v[4:5], v[4:5], v[200:201]
	v_pk_mul_f32 v[0:1], v[0:1], v[210:211]
	v_pk_mul_f32 v[30:31], v[30:31], v[194:195]
	v_pk_mul_f32 v[26:27], v[26:27], v[198:199]
	v_pk_mul_f32 v[22:23], v[22:23], v[202:203]
	v_pk_mul_f32 v[18:19], v[18:19], v[212:213]
	v_pk_mul_f32 v[28:29], v[28:29], v[192:193]
	v_pk_mul_f32 v[24:25], v[24:25], v[196:197]
	v_pk_mul_f32 v[20:21], v[20:21], v[200:201]
	v_pk_mul_f32 v[16:17], v[16:17], v[210:211]

; __device__ __forceinline__ void finishSM(f32x16& p0, f32x16& p1, float alpha, float& l_reg, bf16x8& pa0, bf16x8& pa1, bf16x8& pa2, bf16x8& pa3) {
; #pragma unroll
;   for (int r = 0; r < 16; ++r) p1[r] = __builtin_amdgcn_exp2f(p1[r]);
;   float ps = 0;
; #pragma unroll
;   for (int r = 0; r < 16; ++r) ps += p0[r];
; #pragma unroll
;   for (int r = 0; r < 16; ++r) ps += p1[r];
;   { auto rr = __builtin_amdgcn_permlane32_swap(__float_as_uint(ps), __float_as_uint(ps), false, false);
;     ps = __uint_as_float(rr[0]) + __uint_as_float(rr[1]); }
;   l_reg = l_reg * alpha + ps;
;     ...
;   PK4(p0, 0, pa0); PK4(p0, 8, pa1); PK4(p1, 0, pa2); PK4(p1, 8, pa3);
;     ...
; }
; template <int DQK> __device__ __forceinline__ void qkt(f32x16& p0, f32x16& p1, const char* Ks, const bf16x8* qr, int r32, int hi) {
;   p0 = f32x16{}; p1 = f32x16{};
; #pragma unroll
;   for (int d0 = 0; d0 < DQK / 16; ++d0) { int cb = (d0 * 16 + hi * 8) * 2;
;     bf16x8 b0 = *reinterpret_cast<const bf16x8*>(Ks + KSWZ(r32, cb));
;     bf16x8 b1 = *reinterpret_cast<const bf16x8*>(Ks + KSWZ(32 + r32, cb));
;     p0 = __builtin_amdgcn_mfma_f32_32x32x16_bf16(b0, qr[d0], p0, 0, 0, 0);
;     p1 = __builtin_amdgcn_mfma_f32_32x32x16_bf16(b1, qr[d0], p1, 0, 0, 0); }
; }
; __device__ __forceinline__ int v_st(int k, int c) { const int kk = (k & ~0xC) | ((k & 4) << 1) | ((k & 8) >> 1); return ((kk >> 3) * 4 + (c >> 5)) * 512 + ((kk & 7) * 32 + (c & 31)) * 2; }
; __device__ __forceinline__ int v_rd_base(int lane) { return ((lane & 3) << 3) | (((lane >> 2) & 3) << 6) | (((lane >> 4) & 1) << 5) | (((lane >> 5) & 1) << 8); }
; template <int OFF> __device__ __forceinline__ s16x4 tr_read(int vb) {
;   s16x4 r; asm volatile("ds_read_b64_tr_b16 %0, %1 offset:%2" : "=&v"(r) : "v"(vb), "i"(OFF) : "memory"); return r;
; }
; template <int D0> __device__ __forceinline__ void pv_one(f32x16& od, int vb, bf16x8 pa0, bf16x8 pa1, bf16x8 pa2, bf16x8 pa3) {
;   const s16x4 l0 = tr_read<v_rd_off(D0, 0, 0)>(vb), h0 = tr_read<v_rd_off(D0, 0, 1)>(vb), l1 = tr_read<v_rd_off(D0, 1, 0)>(vb), h1 = tr_read<v_rd_off(D0, 1, 1)>(vb);
; template <int DQK, int MODE, int ldq, int ldk, int ldv> ...
;     ...
;   SBAR(); qkt<DQK>(pB0, pB1, K_lds + SHM_K, qr, r32, hi);
;   finishSM(pA0, pA1, alA, l_reg, pa0, pa1, pa2, pa3); SBAR();
;   pv_d0(o, vb0, pa0, pa1, pa2, pa3); BIAS(pB0, pB1, NT - 1); partialSM<DQK>(pB0, pB1, m_reg, mnB, alB);
;   __syncthreads(); RESC(alB);
.LBB0_312:
	s_waitcnt vmcnt(0)
	ds_write_b128 v145, v[92:95] offset:16384
	ds_read_b128 v[32:35], v148 offset:49152
	ds_read_b128 v[36:39], v148 offset:57344
	s_waitcnt lgkmcnt(1)
	v_mfma_f32_32x32x16_bf16 v[48:63], v[32:35], v[84:87], 0
	s_waitcnt lgkmcnt(0)
	v_mfma_f32_32x32x16_bf16 v[32:47], v[36:39], v[84:87], 0
	ds_read_b128 v[84:87], v152 offset:49152
	ds_read_b128 v[88:91], v152 offset:57344
	s_waitcnt lgkmcnt(1)
	v_mfma_f32_32x32x16_bf16 v[48:63], v[84:87], v[80:83], v[48:63]
	s_waitcnt lgkmcnt(0)
	v_mfma_f32_32x32x16_bf16 v[32:47], v[88:91], v[80:83], v[32:47]
	ds_read_b128 v[80:83], v151 offset:49152
	ds_read_b128 v[84:87], v151 offset:57344
	v_exp_f32_e32 v88, v100
	v_exp_f32_e32 v89, v101
	s_waitcnt lgkmcnt(1)
	v_mfma_f32_32x32x16_bf16 v[48:63], v[80:83], v[76:79], v[48:63]
	s_waitcnt lgkmcnt(0)
	v_mfma_f32_32x32x16_bf16 v[32:47], v[84:87], v[76:79], v[32:47]
	ds_read_b128 v[76:79], v149 offset:49152
	ds_read_b128 v[80:83], v149 offset:57344
	v_exp_f32_e32 v84, v110
	v_exp_f32_e32 v85, v111
	v_exp_f32_e32 v86, v106
	v_exp_f32_e32 v87, v107
	s_waitcnt lgkmcnt(1)
	v_mfma_f32_32x32x16_bf16 v[48:63], v[76:79], v[72:75], v[48:63]
	s_waitcnt lgkmcnt(0)
	v_mfma_f32_32x32x16_bf16 v[32:47], v[80:83], v[72:75], v[32:47]
	ds_read_b128 v[72:75], v150 offset:49152
	ds_read_b128 v[76:79], v150 offset:57344
	v_exp_f32_e32 v80, v104
	v_exp_f32_e32 v81, v105
	v_exp_f32_e32 v82, v102
	v_exp_f32_e32 v83, v103
	s_waitcnt lgkmcnt(1)
	v_mfma_f32_32x32x16_bf16 v[48:63], v[72:75], v[68:71], v[48:63]
	s_waitcnt lgkmcnt(0)
	v_mfma_f32_32x32x16_bf16 v[32:47], v[76:79], v[68:71], v[32:47]
	ds_read_b128 v[68:71], v153 offset:49152
	ds_read_b128 v[72:75], v153 offset:57344
	v_exp_f32_e32 v76, v112
	v_exp_f32_e32 v77, v113
	v_exp_f32_e32 v78, v108
	v_exp_f32_e32 v79, v109
	s_waitcnt lgkmcnt(1)
	v_mfma_f32_32x32x16_bf16 v[48:63], v[68:71], v[64:67], v[48:63]
	s_waitcnt lgkmcnt(0)
	v_mfma_f32_32x32x16_bf16 v[32:47], v[72:75], v[64:67], v[32:47]
	v_add_f32_e32 v64, 0, v126
	v_add_f32_e32 v64, v160, v64
	v_add_f32_e32 v64, v127, v64
	v_add_f32_e32 v64, v161, v64
	v_add_f32_e32 v64, v158, v64
	v_add_f32_e32 v64, v162, v64
	v_add_f32_e32 v64, v159, v64
	v_add_f32_e32 v64, v163, v64
	v_add_f32_e32 v64, v118, v64
	v_add_f32_e32 v64, v121, v64
	v_add_f32_e32 v64, v119, v64
	v_add_f32_e32 v64, v122, v64
	v_exp_f32_e32 v74, v114
	v_add_f32_e32 v64, v120, v64
	v_exp_f32_e32 v75, v115
	v_add_f32_e32 v64, v123, v64
	v_add_f32_e32 v64, v124, v64
	v_add_f32_e32 v64, v125, v64
	v_add_f32_e32 v64, v74, v64
	v_add_f32_e32 v64, v75, v64
	v_add_f32_e32 v64, v76, v64
	v_add_f32_e32 v64, v77, v64
	v_add_f32_e32 v64, v78, v64
	v_add_f32_e32 v64, v79, v64
	v_add_f32_e32 v64, v80, v64
	v_add_f32_e32 v64, v81, v64
	v_add_f32_e32 v64, v82, v64
	v_add_f32_e32 v64, v83, v64
	v_add_f32_e32 v64, v84, v64
	v_add_f32_e32 v64, v85, v64
	v_add_f32_e32 v64, v86, v64
	v_add_f32_e32 v64, v87, v64
	v_add_f32_e32 v64, v88, v64
	v_add_f32_e32 v64, v89, v64
	v_mov_b32_e32 v65, v64
	v_cvt_pk_bf16_f32 v66, v126, v160
	v_cvt_pk_bf16_f32 v67, v127, v161
	v_cvt_pk_bf16_f32 v68, v158, v162
	v_cvt_pk_bf16_f32 v69, v159, v163
	s_nop 1
	v_permlane32_swap_b32_e32 v64, v65
	v_permlane32_swap_b32_e32 v66, v68
	v_permlane32_swap_b32_e32 v67, v69
	v_cvt_pk_bf16_f32 v70, v118, v121
	v_cvt_pk_bf16_f32 v71, v119, v122
	v_cvt_pk_bf16_f32 v72, v120, v123
	v_cvt_pk_bf16_f32 v73, v124, v125
	v_cvt_pk_bf16_f32 v74, v74, v75
	v_cvt_pk_bf16_f32 v75, v76, v77
	v_cvt_pk_bf16_f32 v76, v78, v79
	v_cvt_pk_bf16_f32 v77, v80, v81
	v_cvt_pk_bf16_f32 v78, v82, v83
	v_cvt_pk_bf16_f32 v79, v84, v85
	v_cvt_pk_bf16_f32 v80, v86, v87
	v_cvt_pk_bf16_f32 v81, v88, v89
	s_nop 0
	v_permlane32_swap_b32_e32 v70, v72
	v_permlane32_swap_b32_e32 v71, v73
	v_permlane32_swap_b32_e32 v74, v76
	v_permlane32_swap_b32_e32 v75, v77
	v_permlane32_swap_b32_e32 v78, v80
	v_permlane32_swap_b32_e32 v79, v81
	ds_read_b64_tr_b16 v[82:83], v144 offset:0
	ds_read_b64_tr_b16 v[84:85], v144 offset:0x800
	ds_read_b64_tr_b16 v[86:87], v144 offset:0x1000
	ds_read_b64_tr_b16 v[88:89], v144 offset:0x1800
	ds_read_b64_tr_b16 v[90:91], v144 offset:0x2000
	ds_read_b64_tr_b16 v[92:93], v144 offset:0x2800
	ds_read_b64_tr_b16 v[94:95], v144 offset:0x3000
	ds_read_b64_tr_b16 v[96:97], v144 offset:0x3800
	s_waitcnt lgkmcnt(0)
	s_nop 0
	v_mfma_f32_32x32x16_bf16 v[0:15], v[66:69], v[82:85], v[0:15]
	ds_read_b64_tr_b16 v[82:83], v144 offset:0x200
	ds_read_b64_tr_b16 v[84:85], v144 offset:0xa00
	v_mfma_f32_32x32x16_bf16 v[0:15], v[70:73], v[86:89], v[0:15]
	ds_read_b64_tr_b16 v[86:87], v144 offset:0x1200
	ds_read_b64_tr_b16 v[88:89], v144 offset:0x1a00
	v_mfma_f32_32x32x16_bf16 v[0:15], v[74:77], v[90:93], v[0:15]
	ds_read_b64_tr_b16 v[90:91], v144 offset:0x2200
	ds_read_b64_tr_b16 v[92:93], v144 offset:0x2a00
	v_mfma_f32_32x32x16_bf16 v[0:15], v[78:81], v[94:97], v[0:15]
	ds_read_b64_tr_b16 v[94:95], v144 offset:0x3200
	ds_read_b64_tr_b16 v[96:97], v144 offset:0x3a00
	s_waitcnt lgkmcnt(0)
	v_mfma_f32_32x32x16_bf16 v[16:31], v[66:69], v[82:85], v[16:31]
	v_max_f32_e32 v66, v49, v49
	v_max_f32_e32 v67, v48, v48
	v_max_f32_e32 v66, v67, v66
	v_max3_f32 v66, v66, v50, v51
	v_max3_f32 v66, v66, v52, v53
	v_max3_f32 v66, v66, v54, v55
	v_max3_f32 v66, v66, v56, v57
	v_max3_f32 v66, v66, v58, v59
	v_max3_f32 v66, v66, v60, v61
	v_mfma_f32_32x32x16_bf16 v[16:31], v[70:73], v[86:89], v[16:31]
	v_max3_f32 v66, v66, v62, v63
	v_max3_f32 v66, v66, v32, v33
	v_max3_f32 v66, v66, v34, v35
	v_max3_f32 v66, v66, v36, v37
	v_max3_f32 v66, v66, v38, v39
	v_max3_f32 v66, v66, v40, v41
	v_max3_f32 v66, v66, v42, v43
	v_max3_f32 v66, v66, v44, v45
	v_mfma_f32_32x32x16_bf16 v[16:31], v[74:77], v[90:93], v[16:31]
	v_max3_f32 v66, v66, v46, v47
	v_mov_b32_e32 v67, v66
	s_nop 1
	v_permlane32_swap_b32_e32 v66, v67
	v_max_f32_e32 v67, v67, v67
	v_max_f32_e32 v66, v66, v66
	v_max_f32_e32 v66, v66, v67
	v_sub_f32_e32 v67, v66, v116
	v_cmp_ge_f32_e32 vcc, s80, v67
	v_max_f32_e32 v67, v116, v116
	v_max_f32_e32 v67, v67, v66
	v_mfma_f32_32x32x16_bf16 v[16:31], v[78:81], v[94:97], v[16:31]
	v_sub_f32_e32 v66, v116, v67
	v_mul_f32_e32 v66, 0x3e16c740, v66
	v_exp_f32_e32 v66, v66
	s_cmp_eq_u64 vcc, exec
	s_cselect_b64 s[0:1], -1, 0
	v_cndmask_b32_e64 v66, v66, 1.0, s[0:1]
	v_cmp_gt_f32_e32 vcc, 1.0, v66
	s_barrier
	s_cbranch_vccz .LBB0_316
	s_and_saveexec_b64 s[10:11], s[4:5]
	ds_write_b32 v141, v66 offset:128
	s_or_b64 exec, exec, s[10:11]
	s_waitcnt lgkmcnt(0)
	ds_read_b128 v[68:71], v129 offset:224
	ds_read_b128 v[72:75], v129 offset:192
	ds_read_b128 v[76:79], v129 offset:160
	ds_read_b128 v[80:83], v129 offset:128
	s_waitcnt lgkmcnt(3)
	v_pk_mul_f32 v[14:15], v[14:15], v[70:71]
	s_waitcnt lgkmcnt(2)
	v_pk_mul_f32 v[10:11], v[10:11], v[74:75]
	s_waitcnt lgkmcnt(1)
	v_pk_mul_f32 v[6:7], v[6:7], v[78:79]
	s_waitcnt lgkmcnt(0)
	v_pk_mul_f32 v[2:3], v[2:3], v[82:83]
	v_pk_mul_f32 v[12:13], v[12:13], v[68:69]
	v_pk_mul_f32 v[8:9], v[8:9], v[72:73]
	v_pk_mul_f32 v[4:5], v[4:5], v[76:77]
	v_pk_mul_f32 v[0:1], v[0:1], v[80:81]
	v_pk_mul_f32 v[30:31], v[30:31], v[70:71]
	v_pk_mul_f32 v[26:27], v[26:27], v[74:75]
	v_pk_mul_f32 v[22:23], v[22:23], v[78:79]
	v_pk_mul_f32 v[18:19], v[18:19], v[82:83]
	v_pk_mul_f32 v[28:29], v[28:29], v[68:69]
	v_pk_mul_f32 v[24:25], v[24:25], v[72:73]
	v_pk_mul_f32 v[20:21], v[20:21], v[76:77]
	v_pk_mul_f32 v[16:17], v[16:17], v[80:81]
